# GEMM K-loops: 3 trailing MFMAs (instead of 2) after the early post-MMA barrier in phases 1/3/5/7
# baseline (speedup 1.0000x reference)
; #define PG8_STAGE(bufoff, gbase, voff) do { _Pragma("unroll") for (int _i = 0; _i < 2; ++_i) \
;         __builtin_amdgcn_global_load_lds((const unsigned*)((const char*)(gbase) + (voff)[_i]), (LAS unsigned*)(lds + (bufoff) + ldsw + _i * 8192), 16, 0, 0); } while (0)
; #define PG8_LDA(dst, b, h) do { _Pragma("unroll") for (int m = 0; m < 4; ++m) _Pragma("unroll") for (int k = 0; k < 2; ++k) dst[m][k] = *(const LAS bf16x8*)(lds + PG8_SA(b, h) + aoff + m * 2048 + k * 1024); } while (0)
; #define PG8_LDB(dst, b, h) do { _Pragma("unroll") for (int n = 0; n < 2; ++n) _Pragma("unroll") for (int k = 0; k < 2; ++k) dst[n][k] = *(const LAS bf16x8*)(lds + PG8_SB(b, h) + boff + n * 2048 + k * 1024); } while (0)
; #define PG8_MMA(ai, bj, At, Bt) do { __builtin_amdgcn_s_setprio(1); _Pragma("unroll") for (int m = 0; m < 4; ++m) _Pragma("unroll") for (int n = 0; n < 2; ++n) _Pragma("unroll") for (int k = 0; k < 2; ++k) \
;         acc[ai][bj][m][n] = __builtin_amdgcn_mfma_f32_16x16x32_bf16(Bt[n][k], At[m][k], acc[ai][bj][m][n], 0, 0, 0); __builtin_amdgcn_s_setprio(0); } while (0)
; #define PG8_WAIT_V(n) asm volatile("s_waitcnt vmcnt(" #n ")" ::: "memory")
; #define PG8_WAIT_L(n) asm volatile("s_waitcnt lgkmcnt(" #n ")" ::: "memory")
; #define PG8_BAR __builtin_amdgcn_s_barrier()
; #define PG8_SCHED __builtin_amdgcn_sched_barrier(0)
; template <class Epi, class Sched, int LD>
; __device__ __forceinline__ void gemm_phase(LAS unsigned char* lds, const Gemm g, const Sched& S, const Epi& E) {
;     ...
;             PG8_LDB(B0, 0, 0); PG8_SCHED; PG8_LDA(At, 0, 0); PG8_STAGE(PG8_SA(1, 1), a1 + hstep, voffA);
;             PG8_WAIT_L(8); PG8_BAR; PG8_WAIT_L(0); PG8_MMA(0, 0, At, B0); PG8_BAR; PG8_SCHED;
;             PG8_LDB(B1, 0, 1); PG8_STAGE(PG8_SB(0, 0), b2, voffB);
;             PG8_BAR; PG8_WAIT_L(0); PG8_MMA(0, 1, At, B1); PG8_BAR;
;             PG8_LDA(At, 0, 1); PG8_STAGE(PG8_SA(0, 0), a2, voffA);
;             PG8_BAR; PG8_WAIT_L(0); PG8_MMA(1, 0, At, B0); PG8_BAR; PG8_SCHED;
;             PG8_STAGE(PG8_SB(0, 1), b2 + hstep, voffB);
;             PG8_WAIT_V(6); PG8_BAR; PG8_MMA(1, 1, At, B1); PG8_BAR;
.LBB0_58:
	s_add_i32 s71, s4, 2
	s_add_u32 s48, s46, 0x4000
	s_addc_u32 s5, s47, 0
	s_cmp_eq_u32 s68, s4
	s_cselect_b32 s4, s42, s48
	s_cselect_b32 s5, s43, s5
	s_cselect_b32 s48, s44, s69
	s_cselect_b32 s49, s45, s70
	s_add_u32 s50, s4, 0x8000
	s_addc_u32 s51, s5, 0
	s_add_i32 s72, 0, 0x10000
	s_add_i32 m0, s39, 0xc000
	ds_read_b128 v[180:183], v148
	ds_read_b128 v[184:187], v148 offset:1024
	ds_read_b128 v[188:191], v148 offset:2048
	ds_read_b128 v[192:195], v148 offset:3072
	ds_read_b128 v[196:199], v148 offset:4096
	ds_read_b128 v[200:203], v148 offset:5120
	ds_read_b128 v[204:207], v148 offset:6144
	ds_read_b128 v[208:211], v148 offset:7168
	global_load_lds_dwordx4 v132, s[46:47]
	s_add_i32 m0, s39, 0xe000
	s_nop 0
	global_load_lds_dwordx4 v138, s[46:47]
	s_waitcnt lgkmcnt(8)
	s_barrier
	s_waitcnt lgkmcnt(0)
	s_setprio 0
	v_mfma_f32_16x16x32_bf16 v[128:131], v[140:143], v[180:183], v[128:131]
	v_mfma_f32_16x16x32_bf16 v[124:127], v[154:157], v[180:183], v[124:127]
	v_mfma_f32_16x16x32_bf16 v[112:115], v[140:143], v[188:191], v[112:115]
	v_mfma_f32_16x16x32_bf16 v[108:111], v[154:157], v[188:191], v[108:111]
	v_mfma_f32_16x16x32_bf16 v[96:99], v[140:143], v[196:199], v[96:99]
	v_mfma_f32_16x16x32_bf16 v[92:95], v[154:157], v[196:199], v[92:95]
	v_mfma_f32_16x16x32_bf16 v[80:83], v[140:143], v[204:207], v[80:83]
	v_mfma_f32_16x16x32_bf16 v[76:79], v[154:157], v[204:207], v[76:79]
	v_mfma_f32_16x16x32_bf16 v[128:131], v[150:153], v[184:187], v[128:131]
	v_mfma_f32_16x16x32_bf16 v[124:127], v[176:179], v[184:187], v[124:127]
	v_mfma_f32_16x16x32_bf16 v[112:115], v[150:153], v[192:195], v[112:115]
	v_mfma_f32_16x16x32_bf16 v[108:111], v[176:179], v[192:195], v[108:111]
	v_mfma_f32_16x16x32_bf16 v[96:99], v[150:153], v[200:203], v[96:99]
	s_barrier
	s_setprio 3
	v_mfma_f32_16x16x32_bf16 v[92:95], v[176:179], v[200:203], v[92:95]
	v_mfma_f32_16x16x32_bf16 v[80:83], v[150:153], v[208:211], v[80:83]
	v_mfma_f32_16x16x32_bf16 v[76:79], v[176:179], v[208:211], v[76:79]
	s_setprio 2
	s_add_i32 s74, 0, 0x14000
	s_add_i32 s72, s72, s29
	ds_read_b128 v[212:215], v228 offset:16384
	ds_read_b128 v[216:219], v228 offset:17408
	ds_read_b128 v[220:223], v228 offset:18432
	ds_read_b128 v[224:227], v228 offset:19456
	s_mov_b32 m0, s72
	s_nop 0
	global_load_lds_dwordx4 v132, s[48:49]
	s_add_i32 m0, s72, 0x2000
	s_nop 0
	global_load_lds_dwordx4 v138, s[48:49]
	s_barrier
	s_waitcnt lgkmcnt(0)
	s_setprio 0
	v_mfma_f32_16x16x32_bf16 v[120:123], v[212:215], v[180:183], v[120:123]
	v_mfma_f32_16x16x32_bf16 v[116:119], v[220:223], v[180:183], v[116:119]
	v_mfma_f32_16x16x32_bf16 v[104:107], v[212:215], v[188:191], v[104:107]
	v_mfma_f32_16x16x32_bf16 v[100:103], v[220:223], v[188:191], v[100:103]
	v_mfma_f32_16x16x32_bf16 v[88:91], v[212:215], v[196:199], v[88:91]
	v_mfma_f32_16x16x32_bf16 v[84:87], v[220:223], v[196:199], v[84:87]
	v_mfma_f32_16x16x32_bf16 v[72:75], v[212:215], v[204:207], v[72:75]
	v_mfma_f32_16x16x32_bf16 v[68:71], v[220:223], v[204:207], v[68:71]
	v_mfma_f32_16x16x32_bf16 v[120:123], v[216:219], v[184:187], v[120:123]
	v_mfma_f32_16x16x32_bf16 v[116:119], v[224:227], v[184:187], v[116:119]
	v_mfma_f32_16x16x32_bf16 v[104:107], v[216:219], v[192:195], v[104:107]
	v_mfma_f32_16x16x32_bf16 v[100:103], v[224:227], v[192:195], v[100:103]
	v_mfma_f32_16x16x32_bf16 v[88:91], v[216:219], v[200:203], v[88:91]
	v_mfma_f32_16x16x32_bf16 v[84:87], v[224:227], v[200:203], v[84:87]
	v_mfma_f32_16x16x32_bf16 v[72:75], v[216:219], v[208:211], v[72:75]
	v_mfma_f32_16x16x32_bf16 v[68:71], v[224:227], v[208:211], v[68:71]
	s_barrier
	s_setprio 2
	s_mov_b32 m0, s39
	ds_read_b128 v[180:183], v148 offset:16384
	ds_read_b128 v[184:187], v148 offset:17408
	ds_read_b128 v[188:191], v148 offset:18432
	ds_read_b128 v[192:195], v148 offset:19456
	ds_read_b128 v[196:199], v148 offset:20480
	ds_read_b128 v[200:203], v148 offset:21504
	ds_read_b128 v[204:207], v148 offset:22528
	ds_read_b128 v[208:211], v148 offset:23552
	global_load_lds_dwordx4 v132, s[4:5]
	s_mov_b32 m0, s52
	s_nop 0
	global_load_lds_dwordx4 v138, s[4:5]
	s_waitcnt vmcnt(10)
	s_barrier
	s_waitcnt lgkmcnt(0)
	s_setprio 0
	v_mfma_f32_16x16x32_bf16 v[64:67], v[140:143], v[180:183], v[64:67]
	v_mfma_f32_16x16x32_bf16 v[60:63], v[154:157], v[180:183], v[60:63]
	v_mfma_f32_16x16x32_bf16 v[48:51], v[140:143], v[188:191], v[48:51]
	v_mfma_f32_16x16x32_bf16 v[44:47], v[154:157], v[188:191], v[44:47]
	v_mfma_f32_16x16x32_bf16 v[32:35], v[140:143], v[196:199], v[32:35]
	v_mfma_f32_16x16x32_bf16 v[28:31], v[154:157], v[196:199], v[28:31]
	v_mfma_f32_16x16x32_bf16 v[16:19], v[140:143], v[204:207], v[16:19]
	v_mfma_f32_16x16x32_bf16 v[12:15], v[154:157], v[204:207], v[12:15]
	v_mfma_f32_16x16x32_bf16 v[64:67], v[150:153], v[184:187], v[64:67]
	v_mfma_f32_16x16x32_bf16 v[60:63], v[176:179], v[184:187], v[60:63]
	v_mfma_f32_16x16x32_bf16 v[48:51], v[150:153], v[192:195], v[48:51]
	v_mfma_f32_16x16x32_bf16 v[44:47], v[176:179], v[192:195], v[44:47]
	v_mfma_f32_16x16x32_bf16 v[32:35], v[150:153], v[200:203], v[32:35]
	s_barrier
	s_setprio 3
	v_mfma_f32_16x16x32_bf16 v[28:31], v[176:179], v[200:203], v[28:31]
	v_mfma_f32_16x16x32_bf16 v[16:19], v[150:153], v[208:211], v[16:19]
	v_mfma_f32_16x16x32_bf16 v[12:15], v[176:179], v[208:211], v[12:15]
	s_setprio 2
	ds_read_b128 v[140:143], v228 offset:32768
	ds_read_b128 v[150:153], v228 offset:33792
	ds_read_b128 v[154:157], v228 offset:34816
	ds_read_b128 v[176:179], v228 offset:35840
	s_add_u32 s72, s48, 0x4000
	s_addc_u32 s73, s49, 0
	s_add_i32 s74, s74, s29
	s_mov_b32 m0, s74
	s_nop 0
	global_load_lds_dwordx4 v132, s[72:73]
	s_add_i32 m0, s74, 0x2000
	s_nop 0
	global_load_lds_dwordx4 v138, s[72:73]
	s_waitcnt vmcnt(6)
	s_barrier
; #define PG8_STAGE(bufoff, gbase, voff) do { _Pragma("unroll") for (int _i = 0; _i < 2; ++_i) \
;         __builtin_amdgcn_global_load_lds((const unsigned*)((const char*)(gbase) + (voff)[_i]), (LAS unsigned*)(lds + (bufoff) + ldsw + _i * 8192), 16, 0, 0); } while (0)
; #define PG8_LDA(dst, b, h) do { _Pragma("unroll") for (int m = 0; m < 4; ++m) _Pragma("unroll") for (int k = 0; k < 2; ++k) dst[m][k] = *(const LAS bf16x8*)(lds + PG8_SA(b, h) + aoff + m * 2048 + k * 1024); } while (0)
; #define PG8_LDB(dst, b, h) do { _Pragma("unroll") for (int n = 0; n < 2; ++n) _Pragma("unroll") for (int k = 0; k < 2; ++k) dst[n][k] = *(const LAS bf16x8*)(lds + PG8_SB(b, h) + boff + n * 2048 + k * 1024); } while (0)
; #define PG8_MMA(ai, bj, At, Bt) do { __builtin_amdgcn_s_setprio(1); _Pragma("unroll") for (int m = 0; m < 4; ++m) _Pragma("unroll") for (int n = 0; n < 2; ++n) _Pragma("unroll") for (int k = 0; k < 2; ++k) \
;         acc[ai][bj][m][n] = __builtin_amdgcn_mfma_f32_16x16x32_bf16(Bt[n][k], At[m][k], acc[ai][bj][m][n], 0, 0, 0); __builtin_amdgcn_s_setprio(0); } while (0)
; #define PG8_WAIT_V(n) asm volatile("s_waitcnt vmcnt(" #n ")" ::: "memory")
; #define PG8_WAIT_L(n) asm volatile("s_waitcnt lgkmcnt(" #n ")" ::: "memory")
; #define PG8_BAR __builtin_amdgcn_s_barrier()
; #define PG8_SCHED __builtin_amdgcn_sched_barrier(0)
; template <class Epi, class Sched, int LD>
; __device__ __forceinline__ void gemm_phase(LAS unsigned char* lds, const Gemm g, const Sched& S, const Epi& E) {
;     ...
;             PG8_WAIT_V(6); PG8_BAR; PG8_MMA(1, 1, At, B1); PG8_BAR;
;             PG8_LDB(B0, 1, 0); PG8_SCHED; PG8_LDA(At, 1, 0); PG8_STAGE(PG8_SA(0, 1), a2 + hstep, voffA);
;             PG8_WAIT_L(8); PG8_BAR; PG8_WAIT_L(0); PG8_MMA(0, 0, At, B0); PG8_BAR; PG8_SCHED;
;             PG8_LDB(B1, 1, 1); PG8_STAGE(PG8_SB(1, 0), b3, voffB);
;             PG8_BAR; PG8_WAIT_L(0); PG8_MMA(0, 1, At, B1); PG8_BAR;
;             PG8_LDA(At, 1, 1); PG8_STAGE(PG8_SA(1, 0), a3, voffA);
;             PG8_BAR; PG8_WAIT_L(0); PG8_MMA(1, 0, At, B0); PG8_BAR; PG8_SCHED;
	s_setprio 0
	v_mfma_f32_16x16x32_bf16 v[56:59], v[212:215], v[180:183], v[56:59]
	v_mfma_f32_16x16x32_bf16 v[52:55], v[220:223], v[180:183], v[52:55]
	v_mfma_f32_16x16x32_bf16 v[40:43], v[212:215], v[188:191], v[40:43]
	v_mfma_f32_16x16x32_bf16 v[36:39], v[220:223], v[188:191], v[36:39]
	v_mfma_f32_16x16x32_bf16 v[24:27], v[212:215], v[196:199], v[24:27]
	v_mfma_f32_16x16x32_bf16 v[20:23], v[220:223], v[196:199], v[20:23]
	v_mfma_f32_16x16x32_bf16 v[8:11], v[212:215], v[204:207], v[8:11]
	v_mfma_f32_16x16x32_bf16 v[4:7], v[220:223], v[204:207], v[4:7]
	v_mfma_f32_16x16x32_bf16 v[56:59], v[216:219], v[184:187], v[56:59]
	v_mfma_f32_16x16x32_bf16 v[52:55], v[224:227], v[184:187], v[52:55]
	v_mfma_f32_16x16x32_bf16 v[40:43], v[216:219], v[192:195], v[40:43]
	v_mfma_f32_16x16x32_bf16 v[36:39], v[224:227], v[192:195], v[36:39]
	v_mfma_f32_16x16x32_bf16 v[24:27], v[216:219], v[200:203], v[24:27]
	v_mfma_f32_16x16x32_bf16 v[20:23], v[224:227], v[200:203], v[20:23]
	v_mfma_f32_16x16x32_bf16 v[8:11], v[216:219], v[208:211], v[8:11]
	v_mfma_f32_16x16x32_bf16 v[4:7], v[224:227], v[208:211], v[4:7]
	s_barrier
	s_setprio 2
	s_add_i32 s72, 0, 0x18000
	s_add_u32 s4, s4, 0x4000
	s_addc_u32 s5, s5, 0
	s_mov_b32 m0, s53
	ds_read_b128 v[180:183], v148 offset:32768
	ds_read_b128 v[184:187], v148 offset:33792
	ds_read_b128 v[188:191], v148 offset:34816
	ds_read_b128 v[192:195], v148 offset:35840
	ds_read_b128 v[196:199], v148 offset:36864
	ds_read_b128 v[200:203], v148 offset:37888
	ds_read_b128 v[204:207], v148 offset:38912
	ds_read_b128 v[208:211], v148 offset:39936
	global_load_lds_dwordx4 v132, s[4:5]
	s_mov_b32 m0, s54
	s_nop 0
	global_load_lds_dwordx4 v138, s[4:5]
	s_waitcnt lgkmcnt(8)
	s_barrier
	s_waitcnt lgkmcnt(0)
	s_setprio 0
	v_mfma_f32_16x16x32_bf16 v[128:131], v[140:143], v[180:183], v[128:131]
	v_mfma_f32_16x16x32_bf16 v[124:127], v[154:157], v[180:183], v[124:127]
	v_mfma_f32_16x16x32_bf16 v[112:115], v[140:143], v[188:191], v[112:115]
	v_mfma_f32_16x16x32_bf16 v[108:111], v[154:157], v[188:191], v[108:111]
	v_mfma_f32_16x16x32_bf16 v[96:99], v[140:143], v[196:199], v[96:99]
	v_mfma_f32_16x16x32_bf16 v[92:95], v[154:157], v[196:199], v[92:95]
	v_mfma_f32_16x16x32_bf16 v[80:83], v[140:143], v[204:207], v[80:83]
	v_mfma_f32_16x16x32_bf16 v[76:79], v[154:157], v[204:207], v[76:79]
	v_mfma_f32_16x16x32_bf16 v[128:131], v[150:153], v[184:187], v[128:131]
	v_mfma_f32_16x16x32_bf16 v[124:127], v[176:179], v[184:187], v[124:127]
	v_mfma_f32_16x16x32_bf16 v[112:115], v[150:153], v[192:195], v[112:115]
	v_mfma_f32_16x16x32_bf16 v[108:111], v[176:179], v[192:195], v[108:111]
	v_mfma_f32_16x16x32_bf16 v[96:99], v[150:153], v[200:203], v[96:99]
	s_barrier
	s_setprio 3
	v_mfma_f32_16x16x32_bf16 v[92:95], v[176:179], v[200:203], v[92:95]
	v_mfma_f32_16x16x32_bf16 v[80:83], v[150:153], v[208:211], v[80:83]
	v_mfma_f32_16x16x32_bf16 v[76:79], v[176:179], v[208:211], v[76:79]
	s_setprio 2
	s_add_i32 s73, 0, 0x1c000
	s_add_u32 s4, s48, 0x8000
	s_addc_u32 s5, s49, 0
	s_add_i32 s72, s72, s29
	ds_read_b128 v[212:215], v228 offset:49152
	ds_read_b128 v[216:219], v228 offset:50176
	ds_read_b128 v[220:223], v228 offset:51200
	ds_read_b128 v[224:227], v228 offset:52224
	s_mov_b32 m0, s72
	s_nop 0
	global_load_lds_dwordx4 v132, s[4:5]
	s_add_i32 m0, s72, 0x2000
	s_nop 0
	global_load_lds_dwordx4 v138, s[4:5]
	s_barrier
	s_waitcnt lgkmcnt(0)
	s_setprio 0
	v_mfma_f32_16x16x32_bf16 v[120:123], v[212:215], v[180:183], v[120:123]
	v_mfma_f32_16x16x32_bf16 v[116:119], v[220:223], v[180:183], v[116:119]
	v_mfma_f32_16x16x32_bf16 v[104:107], v[212:215], v[188:191], v[104:107]
	v_mfma_f32_16x16x32_bf16 v[100:103], v[220:223], v[188:191], v[100:103]
	v_mfma_f32_16x16x32_bf16 v[88:91], v[212:215], v[196:199], v[88:91]
	v_mfma_f32_16x16x32_bf16 v[84:87], v[220:223], v[196:199], v[84:87]
	v_mfma_f32_16x16x32_bf16 v[72:75], v[212:215], v[204:207], v[72:75]
	v_mfma_f32_16x16x32_bf16 v[68:71], v[220:223], v[204:207], v[68:71]
	v_mfma_f32_16x16x32_bf16 v[120:123], v[216:219], v[184:187], v[120:123]
	v_mfma_f32_16x16x32_bf16 v[116:119], v[224:227], v[184:187], v[116:119]
	v_mfma_f32_16x16x32_bf16 v[104:107], v[216:219], v[192:195], v[104:107]
	v_mfma_f32_16x16x32_bf16 v[100:103], v[224:227], v[192:195], v[100:103]
	v_mfma_f32_16x16x32_bf16 v[88:91], v[216:219], v[200:203], v[88:91]
	v_mfma_f32_16x16x32_bf16 v[84:87], v[224:227], v[200:203], v[84:87]
	v_mfma_f32_16x16x32_bf16 v[72:75], v[216:219], v[208:211], v[72:75]
	v_mfma_f32_16x16x32_bf16 v[68:71], v[224:227], v[208:211], v[68:71]
	s_barrier
	s_setprio 2
	s_mov_b32 m0, s55
	ds_read_b128 v[180:183], v148 offset:49152
	ds_read_b128 v[184:187], v148 offset:50176
	ds_read_b128 v[188:191], v148 offset:51200
	ds_read_b128 v[192:195], v148 offset:52224
	ds_read_b128 v[196:199], v148 offset:53248
	ds_read_b128 v[200:203], v148 offset:54272
	ds_read_b128 v[204:207], v148 offset:55296
	ds_read_b128 v[208:211], v148 offset:56320
	global_load_lds_dwordx4 v132, s[50:51]
	s_mov_b32 m0, s56
	s_nop 0
	global_load_lds_dwordx4 v138, s[50:51]
	s_waitcnt vmcnt(10)
	s_barrier
	s_waitcnt lgkmcnt(0)
	s_setprio 0
	v_mfma_f32_16x16x32_bf16 v[64:67], v[140:143], v[180:183], v[64:67]
	v_mfma_f32_16x16x32_bf16 v[60:63], v[154:157], v[180:183], v[60:63]
	v_mfma_f32_16x16x32_bf16 v[48:51], v[140:143], v[188:191], v[48:51]
	v_mfma_f32_16x16x32_bf16 v[44:47], v[154:157], v[188:191], v[44:47]
	v_mfma_f32_16x16x32_bf16 v[32:35], v[140:143], v[196:199], v[32:35]
	v_mfma_f32_16x16x32_bf16 v[28:31], v[154:157], v[196:199], v[28:31]
	v_mfma_f32_16x16x32_bf16 v[16:19], v[140:143], v[204:207], v[16:19]
	v_mfma_f32_16x16x32_bf16 v[12:15], v[154:157], v[204:207], v[12:15]
	v_mfma_f32_16x16x32_bf16 v[64:67], v[150:153], v[184:187], v[64:67]
	v_mfma_f32_16x16x32_bf16 v[60:63], v[176:179], v[184:187], v[60:63]
	v_mfma_f32_16x16x32_bf16 v[48:51], v[150:153], v[192:195], v[48:51]
	v_mfma_f32_16x16x32_bf16 v[44:47], v[176:179], v[192:195], v[44:47]
	v_mfma_f32_16x16x32_bf16 v[32:35], v[150:153], v[200:203], v[32:35]
	s_barrier
; #define PG8_STAGE(bufoff, gbase, voff) do { _Pragma("unroll") for (int _i = 0; _i < 2; ++_i) \
;         __builtin_amdgcn_global_load_lds((const unsigned*)((const char*)(gbase) + (voff)[_i]), (LAS unsigned*)(lds + (bufoff) + ldsw + _i * 8192), 16, 0, 0); } while (0)
; #define PG8_MMA(ai, bj, At, Bt) do { __builtin_amdgcn_s_setprio(1); _Pragma("unroll") for (int m = 0; m < 4; ++m) _Pragma("unroll") for (int n = 0; n < 2; ++n) _Pragma("unroll") for (int k = 0; k < 2; ++k) \
;         acc[ai][bj][m][n] = __builtin_amdgcn_mfma_f32_16x16x32_bf16(Bt[n][k], At[m][k], acc[ai][bj][m][n], 0, 0, 0); __builtin_amdgcn_s_setprio(0); } while (0)
; #define PG8_WAIT_V(n) asm volatile("s_waitcnt vmcnt(" #n ")" ::: "memory")
; #define PG8_WAIT_L(n) asm volatile("s_waitcnt lgkmcnt(" #n ")" ::: "memory")
; #define PG8_BAR __builtin_amdgcn_s_barrier()
; #define PG8_SCHED __builtin_amdgcn_sched_barrier(0)
;     __device__ __forceinline__ void operator()(const f32x4 (&acc)[2][2][4][2], const Unit& u, int wr, int wc, int fr, int fq) const {
;     ...
;         } else {
;             float* base = PART + (size_t)u.part * (512 * 2048);
; #pragma unroll
;             for (int ai = 0; ai < 2; ++ai)
; #pragma unroll
;                 for (int m = 0; m < 4; ++m) {
;                     float* rowp = base + (size_t)(row0 - 8192 + ai * HALF + m * 16) * D_MODEL + col0;
; #pragma unroll
;                     for (int bj = 0; bj < 2; ++bj)
; #pragma unroll
;                         for (int n = 0; n < 2; ++n) *(f32x4*)(rowp + bj * HALF + n * 16) = acc[ai][bj][m][n];
;                 }
; template <class Epi, class Sched, int LD>
; __device__ __forceinline__ void gemm_phase(LAS unsigned char* lds, const Gemm g, const Sched& S, const Epi& E) {
;     ...
;             PG8_BAR; PG8_WAIT_L(0); PG8_MMA(1, 0, At, B0); PG8_BAR; PG8_SCHED;
;             PG8_STAGE(PG8_SB(1, 1), b3 + hstep, voffB);
;             PG8_WAIT_V(6); PG8_BAR; PG8_MMA(1, 1, At, B1); PG8_BAR;
	s_setprio 3
	v_mfma_f32_16x16x32_bf16 v[28:31], v[176:179], v[200:203], v[28:31]
	v_mfma_f32_16x16x32_bf16 v[16:19], v[150:153], v[208:211], v[16:19]
	v_mfma_f32_16x16x32_bf16 v[12:15], v[176:179], v[208:211], v[12:15]
	s_setprio 2
	ds_read_b128 v[140:143], v228
	ds_read_b128 v[150:153], v228 offset:1024
	ds_read_b128 v[154:157], v228 offset:2048
	ds_read_b128 v[176:179], v228 offset:3072
	s_add_u32 s4, s48, 0xc000
	s_addc_u32 s5, s49, 0
	s_add_i32 s48, s73, s29
	s_mov_b32 m0, s48
	s_nop 0
	global_load_lds_dwordx4 v132, s[4:5]
	s_add_i32 m0, s48, 0x2000
	s_nop 0
	global_load_lds_dwordx4 v138, s[4:5]
	s_waitcnt vmcnt(6)
	s_barrier
	s_setprio 0
	v_mfma_f32_16x16x32_bf16 v[56:59], v[212:215], v[180:183], v[56:59]
	v_mfma_f32_16x16x32_bf16 v[52:55], v[220:223], v[180:183], v[52:55]
	v_mfma_f32_16x16x32_bf16 v[40:43], v[212:215], v[188:191], v[40:43]
	v_mfma_f32_16x16x32_bf16 v[36:39], v[220:223], v[188:191], v[36:39]
	v_mfma_f32_16x16x32_bf16 v[24:27], v[212:215], v[196:199], v[24:27]
	v_mfma_f32_16x16x32_bf16 v[20:23], v[220:223], v[196:199], v[20:23]
	v_mfma_f32_16x16x32_bf16 v[8:11], v[212:215], v[204:207], v[8:11]
	v_mfma_f32_16x16x32_bf16 v[4:7], v[220:223], v[204:207], v[4:7]
	v_mfma_f32_16x16x32_bf16 v[56:59], v[216:219], v[184:187], v[56:59]
	v_mfma_f32_16x16x32_bf16 v[52:55], v[224:227], v[184:187], v[52:55]
	v_mfma_f32_16x16x32_bf16 v[40:43], v[216:219], v[192:195], v[40:43]
	v_mfma_f32_16x16x32_bf16 v[36:39], v[224:227], v[192:195], v[36:39]
	v_mfma_f32_16x16x32_bf16 v[24:27], v[216:219], v[200:203], v[24:27]
	v_mfma_f32_16x16x32_bf16 v[20:23], v[224:227], v[200:203], v[20:23]
	v_mfma_f32_16x16x32_bf16 v[8:11], v[216:219], v[208:211], v[8:11]
	v_mfma_f32_16x16x32_bf16 v[4:7], v[224:227], v[208:211], v[4:7]
	s_barrier
	s_setprio 2
	s_add_u32 s46, s46, 0x10000
	s_addc_u32 s47, s47, 0
	s_add_u32 s69, s69, 0x10000
	s_addc_u32 s70, s70, 0
	s_cmp_ge_i32 s71, s65
	s_mov_b32 s4, s71
	s_cbranch_scc0 .LBB0_58
	s_setprio 0
	v_lshl_add_u32 v142, s67, 8, v137
	v_lshl_or_b32 v140, s66, 8, v147
	s_mov_b64 s[4:5], -1
	s_cmp_gt_i32 s18, -1
	v_ashrrev_i32_e32 v141, 31, v140
	v_ashrrev_i32_e32 v143, 31, v142
	s_cbranch_scc0 .LBB0_61
	s_lshl_b64 s[4:5], s[18:19], 22
	v_readlane_b32 s18, v252, 10
	s_add_u32 s4, s18, s4
	v_readlane_b32 s18, v252, 11
	s_addc_u32 s5, s18, s5
	v_lshl_add_u64 v[144:145], v[140:141], 2, s[4:5]
	v_lshlrev_b64 v[150:151], 13, v[142:143]
	s_brev_b32 s4, 63
	v_lshl_add_u64 v[144:145], v[144:145], 0, v[150:151]
	s_mov_b32 s5, -1
	v_lshl_add_u64 v[150:151], v[144:145], 0, s[4:5]
	s_brev_b32 s4, 63
	v_add_co_u32_e32 v152, vcc, s4, v144
	s_mov_b32 s4, 0xfc020000
	s_nop 0
	v_addc_co_u32_e32 v153, vcc, -1, v145, vcc
	s_mov_b32 s5, -1
	global_store_dwordx4 v[152:153], v[128:131], off
	global_store_dwordx4 v[150:151], v[124:127], off offset:64
	global_store_dwordx4 v[150:151], v[120:123], off offset:512
	global_store_dwordx4 v[150:151], v[116:119], off offset:576
	v_lshl_add_u64 v[150:151], v[144:145], 0, s[4:5]
	s_mov_b32 s4, 0xfc020000
	v_add_co_u32_e32 v152, vcc, s4, v144
	s_mov_b32 s4, 0xfc040000
	s_nop 0
	v_addc_co_u32_e32 v153, vcc, -1, v145, vcc
	s_mov_b32 s5, -1
	global_store_dwordx4 v[152:153], v[112:115], off
	global_store_dwordx4 v[150:151], v[108:111], off offset:64
	global_store_dwordx4 v[150:151], v[104:107], off offset:512
	global_store_dwordx4 v[150:151], v[100:103], off offset:576
	v_lshl_add_u64 v[150:151], v[144:145], 0, s[4:5]
	s_mov_b32 s4, 0xfc040000
	v_add_co_u32_e32 v152, vcc, s4, v144
	s_mov_b32 s4, 0xfc060000
	s_nop 0
	v_addc_co_u32_e32 v153, vcc, -1, v145, vcc
	s_mov_b32 s5, -1
	global_store_dwordx4 v[152:153], v[96:99], off
	global_store_dwordx4 v[150:151], v[92:95], off offset:64
	global_store_dwordx4 v[150:151], v[88:91], off offset:512
	global_store_dwordx4 v[150:151], v[84:87], off offset:576
	v_lshl_add_u64 v[150:151], v[144:145], 0, s[4:5]
	s_mov_b32 s4, 0xfc060000
	v_add_co_u32_e32 v152, vcc, s4, v144
	s_mov_b32 s4, 0xfc100000
	s_nop 0
	v_addc_co_u32_e32 v153, vcc, -1, v145, vcc
	s_mov_b32 s5, -1
	global_store_dwordx4 v[152:153], v[80:83], off
	global_store_dwordx4 v[150:151], v[76:79], off offset:64
	global_store_dwordx4 v[150:151], v[72:75], off offset:512
	global_store_dwordx4 v[150:151], v[68:71], off offset:576
	v_lshl_add_u64 v[150:151], v[144:145], 0, s[4:5]
	s_mov_b32 s4, 0xfc100000
	v_add_co_u32_e32 v152, vcc, s4, v144
	s_mov_b32 s4, 0xfc120000
	s_nop 0
	v_addc_co_u32_e32 v153, vcc, -1, v145, vcc
	s_mov_b32 s5, -1
	global_store_dwordx4 v[152:153], v[64:67], off
	global_store_dwordx4 v[150:151], v[60:63], off offset:64
	global_store_dwordx4 v[150:151], v[56:59], off offset:512
	global_store_dwordx4 v[150:151], v[52:55], off offset:576
	v_lshl_add_u64 v[150:151], v[144:145], 0, s[4:5]
	s_mov_b32 s4, 0xfc120000
	v_add_co_u32_e32 v152, vcc, s4, v144
	s_mov_b32 s4, 0xfc140000
	s_nop 0
	v_addc_co_u32_e32 v153, vcc, -1, v145, vcc
	s_mov_b32 s5, -1
	global_store_dwordx4 v[152:153], v[48:51], off
	global_store_dwordx4 v[150:151], v[44:47], off offset:64
	global_store_dwordx4 v[150:151], v[40:43], off offset:512
	global_store_dwordx4 v[150:151], v[36:39], off offset:576
	v_lshl_add_u64 v[150:151], v[144:145], 0, s[4:5]
	s_mov_b32 s4, 0xfc140000
	v_add_co_u32_e32 v152, vcc, s4, v144
	s_mov_b32 s4, 0xfc160000
	s_nop 0
	v_addc_co_u32_e32 v153, vcc, -1, v145, vcc
	s_mov_b32 s5, -1
	global_store_dwordx4 v[152:153], v[32:35], off
	global_store_dwordx4 v[150:151], v[28:31], off offset:64
	global_store_dwordx4 v[150:151], v[24:27], off offset:512
	global_store_dwordx4 v[150:151], v[20:23], off offset:576
	v_lshl_add_u64 v[150:151], v[144:145], 0, s[4:5]
	v_add_co_u32_e32 v144, vcc, 0xfc160000, v144
	s_mov_b64 s[4:5], 0
	s_nop 0
	v_addc_co_u32_e32 v145, vcc, -1, v145, vcc
	global_store_dwordx4 v[144:145], v[16:19], off
	global_store_dwordx4 v[150:151], v[12:15], off offset:64
	global_store_dwordx4 v[150:151], v[8:11], off offset:512
	global_store_dwordx4 v[150:151], v[4:7], off offset:576

; #define PG8_STAGE(bufoff, gbase, voff) do { _Pragma("unroll") for (int _i = 0; _i < 2; ++_i) \
;         __builtin_amdgcn_global_load_lds((const unsigned*)((const char*)(gbase) + (voff)[_i]), (LAS unsigned*)(lds + (bufoff) + ldsw + _i * 8192), 16, 0, 0); } while (0)
; #define PG8_LDA(dst, b, h) do { _Pragma("unroll") for (int m = 0; m < 4; ++m) _Pragma("unroll") for (int k = 0; k < 2; ++k) dst[m][k] = *(const LAS bf16x8*)(lds + PG8_SA(b, h) + aoff + m * 2048 + k * 1024); } while (0)
; #define PG8_LDB(dst, b, h) do { _Pragma("unroll") for (int n = 0; n < 2; ++n) _Pragma("unroll") for (int k = 0; k < 2; ++k) dst[n][k] = *(const LAS bf16x8*)(lds + PG8_SB(b, h) + boff + n * 2048 + k * 1024); } while (0)
; #define PG8_MMA(ai, bj, At, Bt) do { __builtin_amdgcn_s_setprio(1); _Pragma("unroll") for (int m = 0; m < 4; ++m) _Pragma("unroll") for (int n = 0; n < 2; ++n) _Pragma("unroll") for (int k = 0; k < 2; ++k) \
;         acc[ai][bj][m][n] = __builtin_amdgcn_mfma_f32_16x16x32_bf16(Bt[n][k], At[m][k], acc[ai][bj][m][n], 0, 0, 0); __builtin_amdgcn_s_setprio(0); } while (0)
; #define PG8_WAIT_V(n) asm volatile("s_waitcnt vmcnt(" #n ")" ::: "memory")
; #define PG8_WAIT_L(n) asm volatile("s_waitcnt lgkmcnt(" #n ")" ::: "memory")
; #define PG8_BAR __builtin_amdgcn_s_barrier()
; #define PG8_SCHED __builtin_amdgcn_sched_barrier(0)
; template <class Epi, class Sched, int LD>
; __device__ __forceinline__ void gemm_phase(LAS unsigned char* lds, const Gemm g, const Sched& S, const Epi& E) {
;     ...
;             PG8_LDB(B0, 0, 0); PG8_SCHED; PG8_LDA(At, 0, 0); PG8_STAGE(PG8_SA(1, 1), a1 + hstep, voffA);
;             PG8_WAIT_L(8); PG8_BAR; PG8_WAIT_L(0); PG8_MMA(0, 0, At, B0); PG8_BAR; PG8_SCHED;
;             PG8_LDB(B1, 0, 1); PG8_STAGE(PG8_SB(0, 0), b2, voffB);
;             PG8_BAR; PG8_WAIT_L(0); PG8_MMA(0, 1, At, B1); PG8_BAR;
;             PG8_LDA(At, 0, 1); PG8_STAGE(PG8_SA(0, 0), a2, voffA);
;             PG8_BAR; PG8_WAIT_L(0); PG8_MMA(1, 0, At, B0); PG8_BAR; PG8_SCHED;
;             PG8_STAGE(PG8_SB(0, 1), b2 + hstep, voffB);
;             PG8_WAIT_V(6); PG8_BAR; PG8_MMA(1, 1, At, B1); PG8_BAR;
.LBB0_501:
	s_add_u32 s4, s54, 0x4000
	s_addc_u32 s5, s55, 0
	s_cmp_eq_u32 s49, 28
	s_cselect_b32 s4, s50, s4
	s_cselect_b32 s5, s51, s5
	s_cselect_b32 s56, s40, s29
	s_cselect_b32 s57, s41, s47
	s_add_u32 s58, s4, 0x8000
	s_addc_u32 s59, s5, 0
	s_add_i32 s69, 0, 0x10000
	s_add_i32 m0, s52, 0xc000
	ds_read_b128 v[180:183], v146
	ds_read_b128 v[184:187], v146 offset:1024
	ds_read_b128 v[188:191], v146 offset:2048
	ds_read_b128 v[192:195], v146 offset:3072
	ds_read_b128 v[196:199], v146 offset:4096
	ds_read_b128 v[200:203], v146 offset:5120
	ds_read_b128 v[204:207], v146 offset:6144
	ds_read_b128 v[208:211], v146 offset:7168
	global_load_lds_dwordx4 v132, s[54:55]
	s_add_i32 m0, s52, 0xe000
	s_nop 0
	global_load_lds_dwordx4 v138, s[54:55]
	s_waitcnt lgkmcnt(8)
	s_barrier
	s_waitcnt lgkmcnt(0)
	s_setprio 0
	v_mfma_f32_16x16x32_bf16 v[128:131], v[148:151], v[180:183], v[128:131]
	v_mfma_f32_16x16x32_bf16 v[124:127], v[156:159], v[180:183], v[124:127]
	v_mfma_f32_16x16x32_bf16 v[120:123], v[148:151], v[188:191], v[120:123]
	v_mfma_f32_16x16x32_bf16 v[116:119], v[156:159], v[188:191], v[116:119]
	v_mfma_f32_16x16x32_bf16 v[104:107], v[148:151], v[196:199], v[104:107]
	v_mfma_f32_16x16x32_bf16 v[100:103], v[156:159], v[196:199], v[100:103]
	v_mfma_f32_16x16x32_bf16 v[88:91], v[148:151], v[204:207], v[88:91]
	v_mfma_f32_16x16x32_bf16 v[84:87], v[156:159], v[204:207], v[84:87]
	v_mfma_f32_16x16x32_bf16 v[128:131], v[152:155], v[184:187], v[128:131]
	v_mfma_f32_16x16x32_bf16 v[124:127], v[176:179], v[184:187], v[124:127]
	v_mfma_f32_16x16x32_bf16 v[120:123], v[152:155], v[192:195], v[120:123]
	v_mfma_f32_16x16x32_bf16 v[116:119], v[176:179], v[192:195], v[116:119]
	v_mfma_f32_16x16x32_bf16 v[104:107], v[152:155], v[200:203], v[104:107]
	s_barrier
	s_setprio 3
	v_mfma_f32_16x16x32_bf16 v[100:103], v[176:179], v[200:203], v[100:103]
	v_mfma_f32_16x16x32_bf16 v[88:91], v[152:155], v[208:211], v[88:91]
	v_mfma_f32_16x16x32_bf16 v[84:87], v[176:179], v[208:211], v[84:87]
	s_setprio 2
	s_add_i32 s72, 0, 0x14000
	s_add_i32 s69, s69, s39
	ds_read_b128 v[212:215], v228 offset:16384
	ds_read_b128 v[216:219], v228 offset:17408
	ds_read_b128 v[220:223], v228 offset:18432
	ds_read_b128 v[224:227], v228 offset:19456
	s_mov_b32 m0, s69
	s_nop 0
	global_load_lds_dwordx4 v132, s[56:57]
	s_add_i32 m0, s69, 0x2000
	s_nop 0
	global_load_lds_dwordx4 v138, s[56:57]
	s_barrier
	s_waitcnt lgkmcnt(0)
	s_setprio 0
	v_mfma_f32_16x16x32_bf16 v[112:115], v[212:215], v[180:183], v[112:115]
	v_mfma_f32_16x16x32_bf16 v[108:111], v[220:223], v[180:183], v[108:111]
	v_mfma_f32_16x16x32_bf16 v[96:99], v[212:215], v[188:191], v[96:99]
	v_mfma_f32_16x16x32_bf16 v[92:95], v[220:223], v[188:191], v[92:95]
	v_mfma_f32_16x16x32_bf16 v[80:83], v[212:215], v[196:199], v[80:83]
	v_mfma_f32_16x16x32_bf16 v[76:79], v[220:223], v[196:199], v[76:79]
	v_mfma_f32_16x16x32_bf16 v[72:75], v[212:215], v[204:207], v[72:75]
	v_mfma_f32_16x16x32_bf16 v[68:71], v[220:223], v[204:207], v[68:71]
	v_mfma_f32_16x16x32_bf16 v[112:115], v[216:219], v[184:187], v[112:115]
	v_mfma_f32_16x16x32_bf16 v[108:111], v[224:227], v[184:187], v[108:111]
	v_mfma_f32_16x16x32_bf16 v[96:99], v[216:219], v[192:195], v[96:99]
	v_mfma_f32_16x16x32_bf16 v[92:95], v[224:227], v[192:195], v[92:95]
	v_mfma_f32_16x16x32_bf16 v[80:83], v[216:219], v[200:203], v[80:83]
	v_mfma_f32_16x16x32_bf16 v[76:79], v[224:227], v[200:203], v[76:79]
	v_mfma_f32_16x16x32_bf16 v[72:75], v[216:219], v[208:211], v[72:75]
	v_mfma_f32_16x16x32_bf16 v[68:71], v[224:227], v[208:211], v[68:71]
	s_barrier
	s_setprio 2
	s_mov_b32 m0, s52
	ds_read_b128 v[180:183], v146 offset:16384
	ds_read_b128 v[184:187], v146 offset:17408
	ds_read_b128 v[188:191], v146 offset:18432
	ds_read_b128 v[192:195], v146 offset:19456
	ds_read_b128 v[196:199], v146 offset:20480
	ds_read_b128 v[200:203], v146 offset:21504
	ds_read_b128 v[204:207], v146 offset:22528
	ds_read_b128 v[208:211], v146 offset:23552
	global_load_lds_dwordx4 v132, s[4:5]
	s_mov_b32 m0, s53
	s_nop 0
	global_load_lds_dwordx4 v138, s[4:5]
	s_waitcnt vmcnt(10)
	s_barrier
	s_waitcnt lgkmcnt(0)
	s_setprio 0
	v_mfma_f32_16x16x32_bf16 v[64:67], v[148:151], v[180:183], v[64:67]
	v_mfma_f32_16x16x32_bf16 v[60:63], v[156:159], v[180:183], v[60:63]
	v_mfma_f32_16x16x32_bf16 v[56:59], v[148:151], v[188:191], v[56:59]
	v_mfma_f32_16x16x32_bf16 v[52:55], v[156:159], v[188:191], v[52:55]
	v_mfma_f32_16x16x32_bf16 v[40:43], v[148:151], v[196:199], v[40:43]
	v_mfma_f32_16x16x32_bf16 v[36:39], v[156:159], v[196:199], v[36:39]
	v_mfma_f32_16x16x32_bf16 v[24:27], v[148:151], v[204:207], v[24:27]
	v_mfma_f32_16x16x32_bf16 v[20:23], v[156:159], v[204:207], v[20:23]
	v_mfma_f32_16x16x32_bf16 v[64:67], v[152:155], v[184:187], v[64:67]
	v_mfma_f32_16x16x32_bf16 v[60:63], v[176:179], v[184:187], v[60:63]
	v_mfma_f32_16x16x32_bf16 v[56:59], v[152:155], v[192:195], v[56:59]
	v_mfma_f32_16x16x32_bf16 v[52:55], v[176:179], v[192:195], v[52:55]
	v_mfma_f32_16x16x32_bf16 v[40:43], v[152:155], v[200:203], v[40:43]
	s_barrier
	s_setprio 3
	v_mfma_f32_16x16x32_bf16 v[36:39], v[176:179], v[200:203], v[36:39]
	v_mfma_f32_16x16x32_bf16 v[24:27], v[152:155], v[208:211], v[24:27]
	v_mfma_f32_16x16x32_bf16 v[20:23], v[176:179], v[208:211], v[20:23]
	s_setprio 2
	ds_read_b128 v[148:151], v228 offset:32768
	ds_read_b128 v[152:155], v228 offset:33792
	ds_read_b128 v[156:159], v228 offset:34816
	ds_read_b128 v[176:179], v228 offset:35840
	s_add_u32 s70, s56, 0x4000
	s_addc_u32 s71, s57, 0
	s_add_i32 s69, s72, s39
	s_mov_b32 m0, s69
	s_nop 0
	global_load_lds_dwordx4 v132, s[70:71]
	s_add_i32 m0, s69, 0x2000
	s_nop 0
	global_load_lds_dwordx4 v138, s[70:71]
	s_waitcnt vmcnt(6)
	s_barrier
; #define PG8_STAGE(bufoff, gbase, voff) do { _Pragma("unroll") for (int _i = 0; _i < 2; ++_i) \
;         __builtin_amdgcn_global_load_lds((const unsigned*)((const char*)(gbase) + (voff)[_i]), (LAS unsigned*)(lds + (bufoff) + ldsw + _i * 8192), 16, 0, 0); } while (0)
; #define PG8_LDA(dst, b, h) do { _Pragma("unroll") for (int m = 0; m < 4; ++m) _Pragma("unroll") for (int k = 0; k < 2; ++k) dst[m][k] = *(const LAS bf16x8*)(lds + PG8_SA(b, h) + aoff + m * 2048 + k * 1024); } while (0)
; #define PG8_LDB(dst, b, h) do { _Pragma("unroll") for (int n = 0; n < 2; ++n) _Pragma("unroll") for (int k = 0; k < 2; ++k) dst[n][k] = *(const LAS bf16x8*)(lds + PG8_SB(b, h) + boff + n * 2048 + k * 1024); } while (0)
; #define PG8_MMA(ai, bj, At, Bt) do { __builtin_amdgcn_s_setprio(1); _Pragma("unroll") for (int m = 0; m < 4; ++m) _Pragma("unroll") for (int n = 0; n < 2; ++n) _Pragma("unroll") for (int k = 0; k < 2; ++k) \
;         acc[ai][bj][m][n] = __builtin_amdgcn_mfma_f32_16x16x32_bf16(Bt[n][k], At[m][k], acc[ai][bj][m][n], 0, 0, 0); __builtin_amdgcn_s_setprio(0); } while (0)
; #define PG8_WAIT_V(n) asm volatile("s_waitcnt vmcnt(" #n ")" ::: "memory")
; #define PG8_WAIT_L(n) asm volatile("s_waitcnt lgkmcnt(" #n ")" ::: "memory")
; #define PG8_BAR __builtin_amdgcn_s_barrier()
; #define PG8_SCHED __builtin_amdgcn_sched_barrier(0)
; template <class Epi, class Sched, int LD>
; __device__ __forceinline__ void gemm_phase(LAS unsigned char* lds, const Gemm g, const Sched& S, const Epi& E) {
;     ...
;             PG8_WAIT_V(6); PG8_BAR; PG8_MMA(1, 1, At, B1); PG8_BAR;
;             PG8_LDB(B0, 1, 0); PG8_SCHED; PG8_LDA(At, 1, 0); PG8_STAGE(PG8_SA(0, 1), a2 + hstep, voffA);
;             PG8_WAIT_L(8); PG8_BAR; PG8_WAIT_L(0); PG8_MMA(0, 0, At, B0); PG8_BAR; PG8_SCHED;
;             PG8_LDB(B1, 1, 1); PG8_STAGE(PG8_SB(1, 0), b3, voffB);
;             PG8_BAR; PG8_WAIT_L(0); PG8_MMA(0, 1, At, B1); PG8_BAR;
;             PG8_LDA(At, 1, 1); PG8_STAGE(PG8_SA(1, 0), a3, voffA);
;             PG8_BAR; PG8_WAIT_L(0); PG8_MMA(1, 0, At, B0); PG8_BAR; PG8_SCHED;
	s_setprio 0
	v_mfma_f32_16x16x32_bf16 v[48:51], v[212:215], v[180:183], v[48:51]
	v_mfma_f32_16x16x32_bf16 v[44:47], v[220:223], v[180:183], v[44:47]
	v_mfma_f32_16x16x32_bf16 v[32:35], v[212:215], v[188:191], v[32:35]
	v_mfma_f32_16x16x32_bf16 v[28:31], v[220:223], v[188:191], v[28:31]
	v_mfma_f32_16x16x32_bf16 v[16:19], v[212:215], v[196:199], v[16:19]
	v_mfma_f32_16x16x32_bf16 v[12:15], v[220:223], v[196:199], v[12:15]
	v_mfma_f32_16x16x32_bf16 v[8:11], v[212:215], v[204:207], v[8:11]
	v_mfma_f32_16x16x32_bf16 v[4:7], v[220:223], v[204:207], v[4:7]
	v_mfma_f32_16x16x32_bf16 v[48:51], v[216:219], v[184:187], v[48:51]
	v_mfma_f32_16x16x32_bf16 v[44:47], v[224:227], v[184:187], v[44:47]
	v_mfma_f32_16x16x32_bf16 v[32:35], v[216:219], v[192:195], v[32:35]
	v_mfma_f32_16x16x32_bf16 v[28:31], v[224:227], v[192:195], v[28:31]
	v_mfma_f32_16x16x32_bf16 v[16:19], v[216:219], v[200:203], v[16:19]
	v_mfma_f32_16x16x32_bf16 v[12:15], v[224:227], v[200:203], v[12:15]
	v_mfma_f32_16x16x32_bf16 v[8:11], v[216:219], v[208:211], v[8:11]
	v_mfma_f32_16x16x32_bf16 v[4:7], v[224:227], v[208:211], v[4:7]
	s_barrier
	s_setprio 2
	s_add_i32 s69, 0, 0x18000
	s_add_u32 s4, s4, 0x4000
	s_addc_u32 s5, s5, 0
	s_mov_b32 m0, s60
	ds_read_b128 v[180:183], v146 offset:32768
	ds_read_b128 v[184:187], v146 offset:33792
	ds_read_b128 v[188:191], v146 offset:34816
	ds_read_b128 v[192:195], v146 offset:35840
	ds_read_b128 v[196:199], v146 offset:36864
	ds_read_b128 v[200:203], v146 offset:37888
	ds_read_b128 v[204:207], v146 offset:38912
	ds_read_b128 v[208:211], v146 offset:39936
	global_load_lds_dwordx4 v132, s[4:5]
	s_mov_b32 m0, s61
	s_nop 0
	global_load_lds_dwordx4 v138, s[4:5]
	s_waitcnt lgkmcnt(8)
	s_barrier
	s_waitcnt lgkmcnt(0)
	s_setprio 0
	v_mfma_f32_16x16x32_bf16 v[128:131], v[148:151], v[180:183], v[128:131]
	v_mfma_f32_16x16x32_bf16 v[124:127], v[156:159], v[180:183], v[124:127]
	v_mfma_f32_16x16x32_bf16 v[120:123], v[148:151], v[188:191], v[120:123]
	v_mfma_f32_16x16x32_bf16 v[116:119], v[156:159], v[188:191], v[116:119]
	v_mfma_f32_16x16x32_bf16 v[104:107], v[148:151], v[196:199], v[104:107]
	v_mfma_f32_16x16x32_bf16 v[100:103], v[156:159], v[196:199], v[100:103]
	v_mfma_f32_16x16x32_bf16 v[88:91], v[148:151], v[204:207], v[88:91]
	v_mfma_f32_16x16x32_bf16 v[84:87], v[156:159], v[204:207], v[84:87]
	v_mfma_f32_16x16x32_bf16 v[128:131], v[152:155], v[184:187], v[128:131]
	v_mfma_f32_16x16x32_bf16 v[124:127], v[176:179], v[184:187], v[124:127]
	v_mfma_f32_16x16x32_bf16 v[120:123], v[152:155], v[192:195], v[120:123]
	v_mfma_f32_16x16x32_bf16 v[116:119], v[176:179], v[192:195], v[116:119]
	v_mfma_f32_16x16x32_bf16 v[104:107], v[152:155], v[200:203], v[104:107]
	s_barrier
	s_setprio 3
	v_mfma_f32_16x16x32_bf16 v[100:103], v[176:179], v[200:203], v[100:103]
	v_mfma_f32_16x16x32_bf16 v[88:91], v[152:155], v[208:211], v[88:91]
	v_mfma_f32_16x16x32_bf16 v[84:87], v[176:179], v[208:211], v[84:87]
	s_setprio 2
	s_add_i32 s70, 0, 0x1c000
	s_add_u32 s4, s56, 0x8000
	s_addc_u32 s5, s57, 0
	s_add_i32 s69, s69, s39
	ds_read_b128 v[212:215], v228 offset:49152
	ds_read_b128 v[216:219], v228 offset:50176
	ds_read_b128 v[220:223], v228 offset:51200
	ds_read_b128 v[224:227], v228 offset:52224
	s_mov_b32 m0, s69
	s_nop 0
	global_load_lds_dwordx4 v132, s[4:5]
	s_add_i32 m0, s69, 0x2000
	s_nop 0
	global_load_lds_dwordx4 v138, s[4:5]
	s_barrier
	s_waitcnt lgkmcnt(0)
	s_setprio 0
	v_mfma_f32_16x16x32_bf16 v[112:115], v[212:215], v[180:183], v[112:115]
	v_mfma_f32_16x16x32_bf16 v[108:111], v[220:223], v[180:183], v[108:111]
	v_mfma_f32_16x16x32_bf16 v[96:99], v[212:215], v[188:191], v[96:99]
	v_mfma_f32_16x16x32_bf16 v[92:95], v[220:223], v[188:191], v[92:95]
	v_mfma_f32_16x16x32_bf16 v[80:83], v[212:215], v[196:199], v[80:83]
	v_mfma_f32_16x16x32_bf16 v[76:79], v[220:223], v[196:199], v[76:79]
	v_mfma_f32_16x16x32_bf16 v[72:75], v[212:215], v[204:207], v[72:75]
	v_mfma_f32_16x16x32_bf16 v[68:71], v[220:223], v[204:207], v[68:71]
	v_mfma_f32_16x16x32_bf16 v[112:115], v[216:219], v[184:187], v[112:115]
	v_mfma_f32_16x16x32_bf16 v[108:111], v[224:227], v[184:187], v[108:111]
	v_mfma_f32_16x16x32_bf16 v[96:99], v[216:219], v[192:195], v[96:99]
	v_mfma_f32_16x16x32_bf16 v[92:95], v[224:227], v[192:195], v[92:95]
	v_mfma_f32_16x16x32_bf16 v[80:83], v[216:219], v[200:203], v[80:83]
	v_mfma_f32_16x16x32_bf16 v[76:79], v[224:227], v[200:203], v[76:79]
	v_mfma_f32_16x16x32_bf16 v[72:75], v[216:219], v[208:211], v[72:75]
	v_mfma_f32_16x16x32_bf16 v[68:71], v[224:227], v[208:211], v[68:71]
	s_barrier
	s_setprio 2
	s_mov_b32 m0, s64
	ds_read_b128 v[180:183], v146 offset:49152
	ds_read_b128 v[184:187], v146 offset:50176
	ds_read_b128 v[188:191], v146 offset:51200
	ds_read_b128 v[192:195], v146 offset:52224
	ds_read_b128 v[196:199], v146 offset:53248
	ds_read_b128 v[200:203], v146 offset:54272
	ds_read_b128 v[204:207], v146 offset:55296
	ds_read_b128 v[208:211], v146 offset:56320
	global_load_lds_dwordx4 v132, s[58:59]
	s_mov_b32 m0, s65
	s_nop 0
	global_load_lds_dwordx4 v138, s[58:59]
	s_waitcnt vmcnt(10)
	s_barrier
; #define PG8_STAGE(bufoff, gbase, voff) do { _Pragma("unroll") for (int _i = 0; _i < 2; ++_i) \
;         __builtin_amdgcn_global_load_lds((const unsigned*)((const char*)(gbase) + (voff)[_i]), (LAS unsigned*)(lds + (bufoff) + ldsw + _i * 8192), 16, 0, 0); } while (0)
; #define PG8_MMA(ai, bj, At, Bt) do { __builtin_amdgcn_s_setprio(1); _Pragma("unroll") for (int m = 0; m < 4; ++m) _Pragma("unroll") for (int n = 0; n < 2; ++n) _Pragma("unroll") for (int k = 0; k < 2; ++k) \
;         acc[ai][bj][m][n] = __builtin_amdgcn_mfma_f32_16x16x32_bf16(Bt[n][k], At[m][k], acc[ai][bj][m][n], 0, 0, 0); __builtin_amdgcn_s_setprio(0); } while (0)
; #define PG8_WAIT_V(n) asm volatile("s_waitcnt vmcnt(" #n ")" ::: "memory")
; #define PG8_WAIT_L(n) asm volatile("s_waitcnt lgkmcnt(" #n ")" ::: "memory")
; #define PG8_BAR __builtin_amdgcn_s_barrier()
; #define PG8_SCHED __builtin_amdgcn_sched_barrier(0)
;     __device__ __forceinline__ void operator()(const f32x4 (&acc)[2][2][4][2], const Unit& u, int wr, int wc, int fr, int fq) const {
;     ...
;         } else if (wc == 0) {
; #pragma unroll
;             for (int ai = 0; ai < 2; ++ai)
; #pragma unroll
;                 for (int m = 0; m < 4; ++m) {
;                     float* rowp = DT + (size_t)(row0 + ai * HALF + m * 16) * 32 + 8 * fq;
;                     *(f32x4*)rowp = acc[ai][0][m][0]; *(f32x4*)(rowp + 4) = acc[ai][0][m][1];
;                 }
; template <class Epi, class Sched, int LD>
; __device__ __forceinline__ void gemm_phase(LAS unsigned char* lds, const Gemm g, const Sched& S, const Epi& E) {
;     ...
;             PG8_BAR; PG8_WAIT_L(0); PG8_MMA(1, 0, At, B0); PG8_BAR; PG8_SCHED;
;             PG8_STAGE(PG8_SB(1, 1), b3 + hstep, voffB);
;             PG8_WAIT_V(6); PG8_BAR; PG8_MMA(1, 1, At, B1); PG8_BAR;
	s_waitcnt lgkmcnt(0)
	s_setprio 0
	v_mfma_f32_16x16x32_bf16 v[64:67], v[148:151], v[180:183], v[64:67]
	v_mfma_f32_16x16x32_bf16 v[60:63], v[156:159], v[180:183], v[60:63]
	v_mfma_f32_16x16x32_bf16 v[56:59], v[148:151], v[188:191], v[56:59]
	v_mfma_f32_16x16x32_bf16 v[52:55], v[156:159], v[188:191], v[52:55]
	v_mfma_f32_16x16x32_bf16 v[40:43], v[148:151], v[196:199], v[40:43]
	v_mfma_f32_16x16x32_bf16 v[36:39], v[156:159], v[196:199], v[36:39]
	v_mfma_f32_16x16x32_bf16 v[24:27], v[148:151], v[204:207], v[24:27]
	v_mfma_f32_16x16x32_bf16 v[20:23], v[156:159], v[204:207], v[20:23]
	v_mfma_f32_16x16x32_bf16 v[64:67], v[152:155], v[184:187], v[64:67]
	v_mfma_f32_16x16x32_bf16 v[60:63], v[176:179], v[184:187], v[60:63]
	v_mfma_f32_16x16x32_bf16 v[56:59], v[152:155], v[192:195], v[56:59]
	v_mfma_f32_16x16x32_bf16 v[52:55], v[176:179], v[192:195], v[52:55]
	v_mfma_f32_16x16x32_bf16 v[40:43], v[152:155], v[200:203], v[40:43]
	s_barrier
	s_setprio 3
	v_mfma_f32_16x16x32_bf16 v[36:39], v[176:179], v[200:203], v[36:39]
	v_mfma_f32_16x16x32_bf16 v[24:27], v[152:155], v[208:211], v[24:27]
	v_mfma_f32_16x16x32_bf16 v[20:23], v[176:179], v[208:211], v[20:23]
	s_setprio 2
	ds_read_b128 v[148:151], v228
	ds_read_b128 v[152:155], v228 offset:1024
	ds_read_b128 v[156:159], v228 offset:2048
	ds_read_b128 v[176:179], v228 offset:3072
	s_add_u32 s4, s56, 0xc000
	s_addc_u32 s5, s57, 0
	s_add_i32 s56, s70, s39
	s_mov_b32 m0, s56
	s_nop 0
	global_load_lds_dwordx4 v132, s[4:5]
	s_add_i32 m0, s56, 0x2000
	s_nop 0
	global_load_lds_dwordx4 v138, s[4:5]
	s_waitcnt vmcnt(6)
	s_barrier
	s_setprio 0
	v_mfma_f32_16x16x32_bf16 v[48:51], v[212:215], v[180:183], v[48:51]
	v_mfma_f32_16x16x32_bf16 v[44:47], v[220:223], v[180:183], v[44:47]
	v_mfma_f32_16x16x32_bf16 v[32:35], v[212:215], v[188:191], v[32:35]
	v_mfma_f32_16x16x32_bf16 v[28:31], v[220:223], v[188:191], v[28:31]
	v_mfma_f32_16x16x32_bf16 v[16:19], v[212:215], v[196:199], v[16:19]
	v_mfma_f32_16x16x32_bf16 v[12:15], v[220:223], v[196:199], v[12:15]
	v_mfma_f32_16x16x32_bf16 v[8:11], v[212:215], v[204:207], v[8:11]
	v_mfma_f32_16x16x32_bf16 v[4:7], v[220:223], v[204:207], v[4:7]
	v_mfma_f32_16x16x32_bf16 v[48:51], v[216:219], v[184:187], v[48:51]
	v_mfma_f32_16x16x32_bf16 v[44:47], v[224:227], v[184:187], v[44:47]
	v_mfma_f32_16x16x32_bf16 v[32:35], v[216:219], v[192:195], v[32:35]
	v_mfma_f32_16x16x32_bf16 v[28:31], v[224:227], v[192:195], v[28:31]
	v_mfma_f32_16x16x32_bf16 v[16:19], v[216:219], v[200:203], v[16:19]
	v_mfma_f32_16x16x32_bf16 v[12:15], v[224:227], v[200:203], v[12:15]
	v_mfma_f32_16x16x32_bf16 v[8:11], v[216:219], v[208:211], v[8:11]
	v_mfma_f32_16x16x32_bf16 v[4:7], v[224:227], v[208:211], v[4:7]
	s_barrier
	s_setprio 2
	s_add_i32 s49, s49, 2
	s_add_u32 s54, s54, 0x10000
	s_addc_u32 s55, s55, 0
	s_add_u32 s29, s29, 0x10000
	s_addc_u32 s47, s47, 0
	s_cmp_gt_u32 s49, 29
	s_cbranch_scc0 .LBB0_501
	s_setprio 0
	v_lshl_add_u32 v142, s68, 8, v137
	s_cmp_gt_i32 s67, 35
	s_mov_b64 s[4:5], -1
	s_cbranch_scc0 .LBB0_506
	s_andn2_b64 vcc, exec, s[42:43]
	s_cbranch_vccnz .LBB0_505
	v_or_b32_e32 v150, 16, v142
	v_ashrrev_i32_e32 v143, 31, v142
	v_ashrrev_i32_e32 v151, 31, v150
	v_lshlrev_b64 v[148:149], 7, v[142:143]
	v_lshlrev_b64 v[150:151], 7, v[150:151]
	v_lshl_add_u64 v[148:149], v[140:141], 0, v[148:149]
	v_lshl_add_u64 v[150:151], v[140:141], 0, v[150:151]
	global_store_dwordx4 v[148:149], v[128:131], off
	global_store_dwordx4 v[148:149], v[124:127], off offset:16
	global_store_dwordx4 v[150:151], v[120:123], off
	global_store_dwordx4 v[150:151], v[116:119], off offset:16
	v_or_b32_e32 v150, 32, v142
	v_ashrrev_i32_e32 v151, 31, v150
	v_lshlrev_b64 v[150:151], 7, v[150:151]
	v_lshl_add_u64 v[150:151], v[140:141], 0, v[150:151]
	global_store_dwordx4 v[150:151], v[104:107], off
	global_store_dwordx4 v[150:151], v[100:103], off offset:16
	v_or_b32_e32 v150, 48, v142
	v_ashrrev_i32_e32 v151, 31, v150
	v_lshlrev_b64 v[150:151], 7, v[150:151]
	v_lshl_add_u64 v[150:151], v[140:141], 0, v[150:151]
	s_mov_b64 s[4:5], 0x4000
	global_store_dwordx4 v[150:151], v[88:91], off
	global_store_dwordx4 v[150:151], v[84:87], off offset:16
	v_lshl_add_u64 v[150:151], v[148:149], 0, s[4:5]
	s_movk_i32 s4, 0x4000
	v_add_co_u32_e32 v152, vcc, s4, v148
	s_mov_b64 s[4:5], 0x4800
	s_nop 0
	v_addc_co_u32_e32 v153, vcc, 0, v149, vcc
	global_store_dwordx4 v[152:153], v[64:67], off
	global_store_dwordx4 v[150:151], v[60:63], off offset:16
	v_lshl_add_u64 v[150:151], v[148:149], 0, s[4:5]
	global_store_dwordx4 v[152:153], v[56:59], off offset:2048
	global_store_dwordx4 v[150:151], v[52:55], off offset:16
	s_mov_b64 s[4:5], 0x5000
	v_add_co_u32_e32 v152, vcc, 0x5000, v148
	v_lshl_add_u64 v[150:151], v[148:149], 0, s[4:5]
	s_nop 0
	v_addc_co_u32_e32 v153, vcc, 0, v149, vcc
	s_mov_b64 s[4:5], 0x5800
	global_store_dwordx4 v[152:153], v[40:43], off
	global_store_dwordx4 v[150:151], v[36:39], off offset:16
	v_lshl_add_u64 v[148:149], v[148:149], 0, s[4:5]
	global_store_dwordx4 v[152:153], v[24:27], off offset:2048
	global_store_dwordx4 v[148:149], v[20:23], off offset:16

; #define PG8_STAGE(bufoff, gbase, voff) do { _Pragma("unroll") for (int _i = 0; _i < 2; ++_i) \
;         __builtin_amdgcn_global_load_lds((const unsigned*)((const char*)(gbase) + (voff)[_i]), (LAS unsigned*)(lds + (bufoff) + ldsw + _i * 8192), 16, 0, 0); } while (0)
; #define PG8_LDA(dst, b, h) do { _Pragma("unroll") for (int m = 0; m < 4; ++m) _Pragma("unroll") for (int k = 0; k < 2; ++k) dst[m][k] = *(const LAS bf16x8*)(lds + PG8_SA(b, h) + aoff + m * 2048 + k * 1024); } while (0)
; #define PG8_LDB(dst, b, h) do { _Pragma("unroll") for (int n = 0; n < 2; ++n) _Pragma("unroll") for (int k = 0; k < 2; ++k) dst[n][k] = *(const LAS bf16x8*)(lds + PG8_SB(b, h) + boff + n * 2048 + k * 1024); } while (0)
; #define PG8_MMA(ai, bj, At, Bt) do { __builtin_amdgcn_s_setprio(1); _Pragma("unroll") for (int m = 0; m < 4; ++m) _Pragma("unroll") for (int n = 0; n < 2; ++n) _Pragma("unroll") for (int k = 0; k < 2; ++k) \
;         acc[ai][bj][m][n] = __builtin_amdgcn_mfma_f32_16x16x32_bf16(Bt[n][k], At[m][k], acc[ai][bj][m][n], 0, 0, 0); __builtin_amdgcn_s_setprio(0); } while (0)
; #define PG8_WAIT_V(n) asm volatile("s_waitcnt vmcnt(" #n ")" ::: "memory")
; #define PG8_WAIT_L(n) asm volatile("s_waitcnt lgkmcnt(" #n ")" ::: "memory")
; #define PG8_BAR __builtin_amdgcn_s_barrier()
; #define PG8_SCHED __builtin_amdgcn_sched_barrier(0)
; template <class Epi, class Sched, int LD>
; __device__ __forceinline__ void gemm_phase(LAS unsigned char* lds, const Gemm g, const Sched& S, const Epi& E) {
;     ...
;             PG8_LDB(B0, 0, 0); PG8_SCHED; PG8_LDA(At, 0, 0); PG8_STAGE(PG8_SA(1, 1), a1 + hstep, voffA);
;             PG8_WAIT_L(8); PG8_BAR; PG8_WAIT_L(0); PG8_MMA(0, 0, At, B0); PG8_BAR; PG8_SCHED;
;             PG8_LDB(B1, 0, 1); PG8_STAGE(PG8_SB(0, 0), b2, voffB);
;             PG8_BAR; PG8_WAIT_L(0); PG8_MMA(0, 1, At, B1); PG8_BAR;
;             PG8_LDA(At, 0, 1); PG8_STAGE(PG8_SA(0, 0), a2, voffA);
;             PG8_BAR; PG8_WAIT_L(0); PG8_MMA(1, 0, At, B0); PG8_BAR; PG8_SCHED;
;             PG8_STAGE(PG8_SB(0, 1), b2 + hstep, voffB);
;             PG8_WAIT_V(6); PG8_BAR; PG8_MMA(1, 1, At, B1); PG8_BAR;
.LBB0_899:
	s_add_u32 s4, s50, 0x4000
	s_addc_u32 s5, s51, 0
	s_cmp_eq_u32 s70, 28
	s_cselect_b32 s4, s48, s4
	s_cselect_b32 s5, s49, s5
	s_cselect_b32 s54, s40, s45
	s_cselect_b32 s55, s41, s47
	s_add_u32 s56, s4, 0x8000
	s_addc_u32 s57, s5, 0
	s_add_i32 s71, 0, 0x10000
	s_add_i32 m0, s29, 0xc000
	ds_read_b128 v[180:183], v144
	ds_read_b128 v[184:187], v144 offset:1024
	ds_read_b128 v[188:191], v144 offset:2048
	ds_read_b128 v[192:195], v144 offset:3072
	ds_read_b128 v[196:199], v144 offset:4096
	ds_read_b128 v[200:203], v144 offset:5120
	ds_read_b128 v[204:207], v144 offset:6144
	ds_read_b128 v[208:211], v144 offset:7168
	global_load_lds_dwordx4 v138, s[50:51]
	s_add_i32 m0, s29, 0xe000
	s_nop 0
	global_load_lds_dwordx4 v140, s[50:51]
	s_waitcnt lgkmcnt(8)
	s_barrier
	s_waitcnt lgkmcnt(0)
	s_setprio 0
	v_mfma_f32_16x16x32_bf16 v[128:131], v[146:149], v[180:183], v[128:131]
	v_mfma_f32_16x16x32_bf16 v[120:123], v[154:157], v[180:183], v[120:123]
	v_mfma_f32_16x16x32_bf16 v[112:115], v[146:149], v[188:191], v[112:115]
	v_mfma_f32_16x16x32_bf16 v[104:107], v[154:157], v[188:191], v[104:107]
	v_mfma_f32_16x16x32_bf16 v[96:99], v[146:149], v[196:199], v[96:99]
	v_mfma_f32_16x16x32_bf16 v[88:91], v[154:157], v[196:199], v[88:91]
	v_mfma_f32_16x16x32_bf16 v[80:83], v[146:149], v[204:207], v[80:83]
	v_mfma_f32_16x16x32_bf16 v[72:75], v[154:157], v[204:207], v[72:75]
	v_mfma_f32_16x16x32_bf16 v[128:131], v[150:153], v[184:187], v[128:131]
	v_mfma_f32_16x16x32_bf16 v[120:123], v[176:179], v[184:187], v[120:123]
	v_mfma_f32_16x16x32_bf16 v[112:115], v[150:153], v[192:195], v[112:115]
	v_mfma_f32_16x16x32_bf16 v[104:107], v[176:179], v[192:195], v[104:107]
	v_mfma_f32_16x16x32_bf16 v[96:99], v[150:153], v[200:203], v[96:99]
	s_barrier
	s_setprio 3
	v_mfma_f32_16x16x32_bf16 v[88:91], v[176:179], v[200:203], v[88:91]
	v_mfma_f32_16x16x32_bf16 v[80:83], v[150:153], v[208:211], v[80:83]
	v_mfma_f32_16x16x32_bf16 v[72:75], v[176:179], v[208:211], v[72:75]
	s_setprio 2
	s_add_i32 s74, 0, 0x14000
	s_add_i32 s71, s71, s28
	s_mov_b32 m0, s71
	ds_read_b128 v[212:215], v228 offset:16384
	ds_read_b128 v[216:219], v228 offset:17408
	ds_read_b128 v[220:223], v228 offset:18432
	ds_read_b128 v[224:227], v228 offset:19456
	global_load_lds_dwordx4 v138, s[54:55]
	s_add_i32 m0, s71, 0x2000
	s_nop 0
	global_load_lds_dwordx4 v140, s[54:55]
	s_barrier
	s_waitcnt lgkmcnt(0)
	s_setprio 0
	v_mfma_f32_16x16x32_bf16 v[124:127], v[212:215], v[180:183], v[124:127]
	v_mfma_f32_16x16x32_bf16 v[116:119], v[220:223], v[180:183], v[116:119]
	v_mfma_f32_16x16x32_bf16 v[108:111], v[212:215], v[188:191], v[108:111]
	v_mfma_f32_16x16x32_bf16 v[100:103], v[220:223], v[188:191], v[100:103]
	v_mfma_f32_16x16x32_bf16 v[92:95], v[212:215], v[196:199], v[92:95]
	v_mfma_f32_16x16x32_bf16 v[84:87], v[220:223], v[196:199], v[84:87]
	v_mfma_f32_16x16x32_bf16 v[76:79], v[212:215], v[204:207], v[76:79]
	v_mfma_f32_16x16x32_bf16 v[68:71], v[220:223], v[204:207], v[68:71]
	v_mfma_f32_16x16x32_bf16 v[124:127], v[216:219], v[184:187], v[124:127]
	v_mfma_f32_16x16x32_bf16 v[116:119], v[224:227], v[184:187], v[116:119]
	v_mfma_f32_16x16x32_bf16 v[108:111], v[216:219], v[192:195], v[108:111]
	v_mfma_f32_16x16x32_bf16 v[100:103], v[224:227], v[192:195], v[100:103]
	v_mfma_f32_16x16x32_bf16 v[92:95], v[216:219], v[200:203], v[92:95]
	v_mfma_f32_16x16x32_bf16 v[84:87], v[224:227], v[200:203], v[84:87]
	v_mfma_f32_16x16x32_bf16 v[76:79], v[216:219], v[208:211], v[76:79]
	v_mfma_f32_16x16x32_bf16 v[68:71], v[224:227], v[208:211], v[68:71]
	s_barrier
	s_setprio 2
	s_mov_b32 m0, s29
	ds_read_b128 v[180:183], v144 offset:16384
	ds_read_b128 v[184:187], v144 offset:17408
	ds_read_b128 v[188:191], v144 offset:18432
	ds_read_b128 v[192:195], v144 offset:19456
	ds_read_b128 v[196:199], v144 offset:20480
	ds_read_b128 v[200:203], v144 offset:21504
	ds_read_b128 v[204:207], v144 offset:22528
	ds_read_b128 v[208:211], v144 offset:23552
	global_load_lds_dwordx4 v138, s[4:5]
	s_mov_b32 m0, s39
	s_nop 0
	global_load_lds_dwordx4 v140, s[4:5]
	s_waitcnt vmcnt(10)
	s_barrier
	s_waitcnt lgkmcnt(0)
	s_setprio 0
	v_mfma_f32_16x16x32_bf16 v[64:67], v[146:149], v[180:183], v[64:67]
	v_mfma_f32_16x16x32_bf16 v[56:59], v[154:157], v[180:183], v[56:59]
	v_mfma_f32_16x16x32_bf16 v[48:51], v[146:149], v[188:191], v[48:51]
	v_mfma_f32_16x16x32_bf16 v[40:43], v[154:157], v[188:191], v[40:43]
	v_mfma_f32_16x16x32_bf16 v[32:35], v[146:149], v[196:199], v[32:35]
	v_mfma_f32_16x16x32_bf16 v[24:27], v[154:157], v[196:199], v[24:27]
	v_mfma_f32_16x16x32_bf16 v[16:19], v[146:149], v[204:207], v[16:19]
	v_mfma_f32_16x16x32_bf16 v[8:11], v[154:157], v[204:207], v[8:11]
	v_mfma_f32_16x16x32_bf16 v[64:67], v[150:153], v[184:187], v[64:67]
	v_mfma_f32_16x16x32_bf16 v[56:59], v[176:179], v[184:187], v[56:59]
	v_mfma_f32_16x16x32_bf16 v[48:51], v[150:153], v[192:195], v[48:51]
	v_mfma_f32_16x16x32_bf16 v[40:43], v[176:179], v[192:195], v[40:43]
	v_mfma_f32_16x16x32_bf16 v[32:35], v[150:153], v[200:203], v[32:35]
	s_barrier
	s_setprio 3
	v_mfma_f32_16x16x32_bf16 v[24:27], v[176:179], v[200:203], v[24:27]
	v_mfma_f32_16x16x32_bf16 v[16:19], v[150:153], v[208:211], v[16:19]
	v_mfma_f32_16x16x32_bf16 v[8:11], v[176:179], v[208:211], v[8:11]
	s_setprio 2
	ds_read_b128 v[146:149], v228 offset:32768
	ds_read_b128 v[150:153], v228 offset:33792
	ds_read_b128 v[154:157], v228 offset:34816
	ds_read_b128 v[176:179], v228 offset:35840
	s_add_u32 s72, s54, 0x4000
	s_addc_u32 s73, s55, 0
	s_add_i32 s71, s74, s28
	s_mov_b32 m0, s71
	s_nop 0
	global_load_lds_dwordx4 v138, s[72:73]
	s_add_i32 m0, s71, 0x2000
	s_nop 0
	global_load_lds_dwordx4 v140, s[72:73]
	s_waitcnt vmcnt(6)
	s_barrier
; #define PG8_STAGE(bufoff, gbase, voff) do { _Pragma("unroll") for (int _i = 0; _i < 2; ++_i) \
;         __builtin_amdgcn_global_load_lds((const unsigned*)((const char*)(gbase) + (voff)[_i]), (LAS unsigned*)(lds + (bufoff) + ldsw + _i * 8192), 16, 0, 0); } while (0)
; #define PG8_LDA(dst, b, h) do { _Pragma("unroll") for (int m = 0; m < 4; ++m) _Pragma("unroll") for (int k = 0; k < 2; ++k) dst[m][k] = *(const LAS bf16x8*)(lds + PG8_SA(b, h) + aoff + m * 2048 + k * 1024); } while (0)
; #define PG8_LDB(dst, b, h) do { _Pragma("unroll") for (int n = 0; n < 2; ++n) _Pragma("unroll") for (int k = 0; k < 2; ++k) dst[n][k] = *(const LAS bf16x8*)(lds + PG8_SB(b, h) + boff + n * 2048 + k * 1024); } while (0)
; #define PG8_MMA(ai, bj, At, Bt) do { __builtin_amdgcn_s_setprio(1); _Pragma("unroll") for (int m = 0; m < 4; ++m) _Pragma("unroll") for (int n = 0; n < 2; ++n) _Pragma("unroll") for (int k = 0; k < 2; ++k) \
;         acc[ai][bj][m][n] = __builtin_amdgcn_mfma_f32_16x16x32_bf16(Bt[n][k], At[m][k], acc[ai][bj][m][n], 0, 0, 0); __builtin_amdgcn_s_setprio(0); } while (0)
; #define PG8_WAIT_V(n) asm volatile("s_waitcnt vmcnt(" #n ")" ::: "memory")
; #define PG8_WAIT_L(n) asm volatile("s_waitcnt lgkmcnt(" #n ")" ::: "memory")
; #define PG8_BAR __builtin_amdgcn_s_barrier()
; #define PG8_SCHED __builtin_amdgcn_sched_barrier(0)
; template <class Epi, class Sched, int LD>
; __device__ __forceinline__ void gemm_phase(LAS unsigned char* lds, const Gemm g, const Sched& S, const Epi& E) {
;     ...
;             PG8_WAIT_V(6); PG8_BAR; PG8_MMA(1, 1, At, B1); PG8_BAR;
;             PG8_LDB(B0, 1, 0); PG8_SCHED; PG8_LDA(At, 1, 0); PG8_STAGE(PG8_SA(0, 1), a2 + hstep, voffA);
;             PG8_WAIT_L(8); PG8_BAR; PG8_WAIT_L(0); PG8_MMA(0, 0, At, B0); PG8_BAR; PG8_SCHED;
;             PG8_LDB(B1, 1, 1); PG8_STAGE(PG8_SB(1, 0), b3, voffB);
;             PG8_BAR; PG8_WAIT_L(0); PG8_MMA(0, 1, At, B1); PG8_BAR;
;             PG8_LDA(At, 1, 1); PG8_STAGE(PG8_SA(1, 0), a3, voffA);
;             PG8_BAR; PG8_WAIT_L(0); PG8_MMA(1, 0, At, B0); PG8_BAR; PG8_SCHED;
	s_setprio 0
	v_mfma_f32_16x16x32_bf16 v[60:63], v[212:215], v[180:183], v[60:63]
	v_mfma_f32_16x16x32_bf16 v[52:55], v[220:223], v[180:183], v[52:55]
	v_mfma_f32_16x16x32_bf16 v[44:47], v[212:215], v[188:191], v[44:47]
	v_mfma_f32_16x16x32_bf16 v[36:39], v[220:223], v[188:191], v[36:39]
	v_mfma_f32_16x16x32_bf16 v[28:31], v[212:215], v[196:199], v[28:31]
	v_mfma_f32_16x16x32_bf16 v[20:23], v[220:223], v[196:199], v[20:23]
	v_mfma_f32_16x16x32_bf16 v[12:15], v[212:215], v[204:207], v[12:15]
	v_mfma_f32_16x16x32_bf16 v[4:7], v[220:223], v[204:207], v[4:7]
	v_mfma_f32_16x16x32_bf16 v[60:63], v[216:219], v[184:187], v[60:63]
	v_mfma_f32_16x16x32_bf16 v[52:55], v[224:227], v[184:187], v[52:55]
	v_mfma_f32_16x16x32_bf16 v[44:47], v[216:219], v[192:195], v[44:47]
	v_mfma_f32_16x16x32_bf16 v[36:39], v[224:227], v[192:195], v[36:39]
	v_mfma_f32_16x16x32_bf16 v[28:31], v[216:219], v[200:203], v[28:31]
	v_mfma_f32_16x16x32_bf16 v[20:23], v[224:227], v[200:203], v[20:23]
	v_mfma_f32_16x16x32_bf16 v[12:15], v[216:219], v[208:211], v[12:15]
	v_mfma_f32_16x16x32_bf16 v[4:7], v[224:227], v[208:211], v[4:7]
	s_barrier
	s_setprio 2
	s_add_i32 s71, 0, 0x18000
	s_add_u32 s4, s4, 0x4000
	s_addc_u32 s5, s5, 0
	s_mov_b32 m0, s52
	ds_read_b128 v[180:183], v144 offset:32768
	ds_read_b128 v[184:187], v144 offset:33792
	ds_read_b128 v[188:191], v144 offset:34816
	ds_read_b128 v[192:195], v144 offset:35840
	ds_read_b128 v[196:199], v144 offset:36864
	ds_read_b128 v[200:203], v144 offset:37888
	ds_read_b128 v[204:207], v144 offset:38912
	ds_read_b128 v[208:211], v144 offset:39936
	global_load_lds_dwordx4 v138, s[4:5]
	s_mov_b32 m0, s53
	s_nop 0
	global_load_lds_dwordx4 v140, s[4:5]
	s_waitcnt lgkmcnt(8)
	s_barrier
	s_waitcnt lgkmcnt(0)
	s_setprio 0
	v_mfma_f32_16x16x32_bf16 v[128:131], v[146:149], v[180:183], v[128:131]
	v_mfma_f32_16x16x32_bf16 v[120:123], v[154:157], v[180:183], v[120:123]
	v_mfma_f32_16x16x32_bf16 v[112:115], v[146:149], v[188:191], v[112:115]
	v_mfma_f32_16x16x32_bf16 v[104:107], v[154:157], v[188:191], v[104:107]
	v_mfma_f32_16x16x32_bf16 v[96:99], v[146:149], v[196:199], v[96:99]
	v_mfma_f32_16x16x32_bf16 v[88:91], v[154:157], v[196:199], v[88:91]
	v_mfma_f32_16x16x32_bf16 v[80:83], v[146:149], v[204:207], v[80:83]
	v_mfma_f32_16x16x32_bf16 v[72:75], v[154:157], v[204:207], v[72:75]
	v_mfma_f32_16x16x32_bf16 v[128:131], v[150:153], v[184:187], v[128:131]
	v_mfma_f32_16x16x32_bf16 v[120:123], v[176:179], v[184:187], v[120:123]
	v_mfma_f32_16x16x32_bf16 v[112:115], v[150:153], v[192:195], v[112:115]
	v_mfma_f32_16x16x32_bf16 v[104:107], v[176:179], v[192:195], v[104:107]
	v_mfma_f32_16x16x32_bf16 v[96:99], v[150:153], v[200:203], v[96:99]
	s_barrier
	s_setprio 3
	v_mfma_f32_16x16x32_bf16 v[88:91], v[176:179], v[200:203], v[88:91]
	v_mfma_f32_16x16x32_bf16 v[80:83], v[150:153], v[208:211], v[80:83]
	v_mfma_f32_16x16x32_bf16 v[72:75], v[176:179], v[208:211], v[72:75]
	s_setprio 2
	s_add_i32 s72, 0, 0x1c000
	s_add_u32 s4, s54, 0x8000
	s_addc_u32 s5, s55, 0
	s_add_i32 s71, s71, s28
	s_mov_b32 m0, s71
	ds_read_b128 v[212:215], v228 offset:49152
	ds_read_b128 v[216:219], v228 offset:50176
	ds_read_b128 v[220:223], v228 offset:51200
	ds_read_b128 v[224:227], v228 offset:52224
	global_load_lds_dwordx4 v138, s[4:5]
	s_add_i32 m0, s71, 0x2000
	s_nop 0
	global_load_lds_dwordx4 v140, s[4:5]
	s_barrier
	s_waitcnt lgkmcnt(0)
	s_setprio 0
	v_mfma_f32_16x16x32_bf16 v[124:127], v[212:215], v[180:183], v[124:127]
	v_mfma_f32_16x16x32_bf16 v[116:119], v[220:223], v[180:183], v[116:119]
	v_mfma_f32_16x16x32_bf16 v[108:111], v[212:215], v[188:191], v[108:111]
	v_mfma_f32_16x16x32_bf16 v[100:103], v[220:223], v[188:191], v[100:103]
	v_mfma_f32_16x16x32_bf16 v[92:95], v[212:215], v[196:199], v[92:95]
	v_mfma_f32_16x16x32_bf16 v[84:87], v[220:223], v[196:199], v[84:87]
	v_mfma_f32_16x16x32_bf16 v[76:79], v[212:215], v[204:207], v[76:79]
	v_mfma_f32_16x16x32_bf16 v[68:71], v[220:223], v[204:207], v[68:71]
	v_mfma_f32_16x16x32_bf16 v[124:127], v[216:219], v[184:187], v[124:127]
	v_mfma_f32_16x16x32_bf16 v[116:119], v[224:227], v[184:187], v[116:119]
	v_mfma_f32_16x16x32_bf16 v[108:111], v[216:219], v[192:195], v[108:111]
	v_mfma_f32_16x16x32_bf16 v[100:103], v[224:227], v[192:195], v[100:103]
	v_mfma_f32_16x16x32_bf16 v[92:95], v[216:219], v[200:203], v[92:95]
	v_mfma_f32_16x16x32_bf16 v[84:87], v[224:227], v[200:203], v[84:87]
	v_mfma_f32_16x16x32_bf16 v[76:79], v[216:219], v[208:211], v[76:79]
	v_mfma_f32_16x16x32_bf16 v[68:71], v[224:227], v[208:211], v[68:71]
	s_barrier
	s_setprio 2
	s_mov_b32 m0, s60
	ds_read_b128 v[180:183], v144 offset:49152
	ds_read_b128 v[184:187], v144 offset:50176
	ds_read_b128 v[188:191], v144 offset:51200
	ds_read_b128 v[192:195], v144 offset:52224
	ds_read_b128 v[196:199], v144 offset:53248
	ds_read_b128 v[200:203], v144 offset:54272
	ds_read_b128 v[204:207], v144 offset:55296
	ds_read_b128 v[208:211], v144 offset:56320
	global_load_lds_dwordx4 v138, s[56:57]
	s_mov_b32 m0, s61
	s_nop 0
	global_load_lds_dwordx4 v140, s[56:57]
	s_waitcnt vmcnt(10)
	s_barrier
	s_waitcnt lgkmcnt(0)
	s_setprio 0
	v_mfma_f32_16x16x32_bf16 v[64:67], v[146:149], v[180:183], v[64:67]
	v_mfma_f32_16x16x32_bf16 v[56:59], v[154:157], v[180:183], v[56:59]
	v_mfma_f32_16x16x32_bf16 v[48:51], v[146:149], v[188:191], v[48:51]
	v_mfma_f32_16x16x32_bf16 v[40:43], v[154:157], v[188:191], v[40:43]
	v_mfma_f32_16x16x32_bf16 v[32:35], v[146:149], v[196:199], v[32:35]
	v_mfma_f32_16x16x32_bf16 v[24:27], v[154:157], v[196:199], v[24:27]
	v_mfma_f32_16x16x32_bf16 v[16:19], v[146:149], v[204:207], v[16:19]
	v_mfma_f32_16x16x32_bf16 v[8:11], v[154:157], v[204:207], v[8:11]
	v_mfma_f32_16x16x32_bf16 v[64:67], v[150:153], v[184:187], v[64:67]
	v_mfma_f32_16x16x32_bf16 v[56:59], v[176:179], v[184:187], v[56:59]
	v_mfma_f32_16x16x32_bf16 v[48:51], v[150:153], v[192:195], v[48:51]
	v_mfma_f32_16x16x32_bf16 v[40:43], v[176:179], v[192:195], v[40:43]
	v_mfma_f32_16x16x32_bf16 v[32:35], v[150:153], v[200:203], v[32:35]
	s_barrier
; __device__ __forceinline__ unsigned cvt_pk_bf16(float lo, float hi) { f32x2 v = {lo, hi}; bf16x2v b = __builtin_convertvector(v, bf16x2v); return __builtin_bit_cast(unsigned, b); }
; __device__ __forceinline__ float silu_f(float x) { return x * __builtin_amdgcn_rcpf(1.f + __expf(-x)); }
; #define PG8_STAGE(bufoff, gbase, voff) do { _Pragma("unroll") for (int _i = 0; _i < 2; ++_i) \
;         __builtin_amdgcn_global_load_lds((const unsigned*)((const char*)(gbase) + (voff)[_i]), (LAS unsigned*)(lds + (bufoff) + ldsw + _i * 8192), 16, 0, 0); } while (0)
; #define PG8_MMA(ai, bj, At, Bt) do { __builtin_amdgcn_s_setprio(1); _Pragma("unroll") for (int m = 0; m < 4; ++m) _Pragma("unroll") for (int n = 0; n < 2; ++n) _Pragma("unroll") for (int k = 0; k < 2; ++k) \
;         acc[ai][bj][m][n] = __builtin_amdgcn_mfma_f32_16x16x32_bf16(Bt[n][k], At[m][k], acc[ai][bj][m][n], 0, 0, 0); __builtin_amdgcn_s_setprio(0); } while (0)
; #define PG8_WAIT_V(n) asm volatile("s_waitcnt vmcnt(" #n ")" ::: "memory")
; #define PG8_WAIT_L(n) asm volatile("s_waitcnt lgkmcnt(" #n ")" ::: "memory")
;     __device__ __forceinline__ void operator()(const f32x4 (&acc)[2][2][4][2], const Unit& u, int wr, int wc, int fr, int fq) const {
;         const int row0 = u.pm * BM + wr * 64 + fr, col0 = u.pn * 128 + wc * 32 + 8 * fq;
; #pragma unroll
;         for (int ai = 0; ai < 2; ++ai)
; #pragma unroll
;             for (int m = 0; m < 4; ++m) {
;                 bf16_t* rowp = O + img_off(row0 + ai * HALF + m * 16, col0, D_FF / 64);
;                 const f32x4 g0 = acc[ai][0][m][0], g1 = acc[ai][0][m][1], u0 = acc[ai][1][m][0], u1 = acc[ai][1][m][1];
;                 u32x4 w;
;                 w.x = cvt_pk_bf16(silu_f(g0[0]) * u0[0], silu_f(g0[1]) * u0[1]); w.y = cvt_pk_bf16(silu_f(g0[2]) * u0[2], silu_f(g0[3]) * u0[3]);
;                 w.z = cvt_pk_bf16(silu_f(g1[0]) * u1[0], silu_f(g1[1]) * u1[1]); w.w = cvt_pk_bf16(silu_f(g1[2]) * u1[2], silu_f(g1[3]) * u1[3]);
;                 *(u32x4*)rowp = w;
; template <class Epi, class Sched, int LD>
; __device__ __forceinline__ void gemm_phase(LAS unsigned char* lds, const Gemm g, const Sched& S, const Epi& E) {
;     ...
;             PG8_BAR; PG8_WAIT_L(0); PG8_MMA(1, 0, At, B0); PG8_BAR; PG8_SCHED;
;             PG8_STAGE(PG8_SB(1, 1), b3 + hstep, voffB);
;             PG8_WAIT_V(6); PG8_BAR; PG8_MMA(1, 1, At, B1); PG8_BAR;
	s_setprio 3
	v_mfma_f32_16x16x32_bf16 v[24:27], v[176:179], v[200:203], v[24:27]
	v_mfma_f32_16x16x32_bf16 v[16:19], v[150:153], v[208:211], v[16:19]
	v_mfma_f32_16x16x32_bf16 v[8:11], v[176:179], v[208:211], v[8:11]
	s_setprio 2
	ds_read_b128 v[146:149], v228
	ds_read_b128 v[150:153], v228 offset:1024
	ds_read_b128 v[154:157], v228 offset:2048
	ds_read_b128 v[176:179], v228 offset:3072
	s_add_u32 s4, s54, 0xc000
	s_addc_u32 s5, s55, 0
	s_add_i32 s54, s72, s28
	s_mov_b32 m0, s54
	s_nop 0
	global_load_lds_dwordx4 v138, s[4:5]
	s_add_i32 m0, s54, 0x2000
	s_nop 0
	global_load_lds_dwordx4 v140, s[4:5]
	s_waitcnt vmcnt(6)
	s_barrier
	s_setprio 0
	v_mfma_f32_16x16x32_bf16 v[60:63], v[212:215], v[180:183], v[60:63]
	v_mfma_f32_16x16x32_bf16 v[52:55], v[220:223], v[180:183], v[52:55]
	v_mfma_f32_16x16x32_bf16 v[44:47], v[212:215], v[188:191], v[44:47]
	v_mfma_f32_16x16x32_bf16 v[36:39], v[220:223], v[188:191], v[36:39]
	v_mfma_f32_16x16x32_bf16 v[28:31], v[212:215], v[196:199], v[28:31]
	v_mfma_f32_16x16x32_bf16 v[20:23], v[220:223], v[196:199], v[20:23]
	v_mfma_f32_16x16x32_bf16 v[12:15], v[212:215], v[204:207], v[12:15]
	v_mfma_f32_16x16x32_bf16 v[4:7], v[220:223], v[204:207], v[4:7]
	v_mfma_f32_16x16x32_bf16 v[60:63], v[216:219], v[184:187], v[60:63]
	v_mfma_f32_16x16x32_bf16 v[52:55], v[224:227], v[184:187], v[52:55]
	v_mfma_f32_16x16x32_bf16 v[44:47], v[216:219], v[192:195], v[44:47]
	v_mfma_f32_16x16x32_bf16 v[36:39], v[224:227], v[192:195], v[36:39]
	v_mfma_f32_16x16x32_bf16 v[28:31], v[216:219], v[200:203], v[28:31]
	v_mfma_f32_16x16x32_bf16 v[20:23], v[224:227], v[200:203], v[20:23]
	v_mfma_f32_16x16x32_bf16 v[12:15], v[216:219], v[208:211], v[12:15]
	v_mfma_f32_16x16x32_bf16 v[4:7], v[224:227], v[208:211], v[4:7]
	s_barrier
	s_setprio 2
	s_add_i32 s70, s70, 2
	s_add_u32 s50, s50, 0x10000
	s_addc_u32 s51, s51, 0
	s_add_u32 s45, s45, 0x10000
	s_addc_u32 s47, s47, 0
	s_cmp_gt_u32 s70, 29
	s_cbranch_scc0 .LBB0_899
	s_setprio 0
	v_mul_f32_e32 v148, 0xbfb8aa3b, v128
	v_mul_f32_e32 v149, 0xbfb8aa3b, v129
	v_exp_f32_e32 v148, v148
	v_exp_f32_e32 v149, v149
	s_lshl_b32 s5, s69, 8
	s_add_i32 s5, s5, s58
	v_add_f32_e32 v148, 1.0, v148
	v_add_f32_e32 v149, 1.0, v149
	v_rcp_f32_e32 v148, v148
	v_rcp_f32_e32 v149, v149
	s_lshl_b32 s4, s68, 7
	s_or_b32 s4, s4, s59
	s_ashr_i32 s45, s5, 8
	v_pk_mul_f32 v[128:129], v[128:129], v[148:149]
	s_ashr_i32 s4, s4, 6
	v_pk_mul_f32 v[124:125], v[128:129], v[124:125]
	s_mulk_i32 s45, 0x58
	v_cvt_pk_bf16_f32 v124, v124, v125
	v_mul_f32_e32 v125, 0xbfb8aa3b, v130
	v_exp_f32_e32 v125, v125
	s_add_i32 s50, s45, s4
	s_ashr_i32 s51, s50, 31
	s_lshl_b64 s[50:51], s[50:51], 15
	v_add_f32_e32 v125, 1.0, v125
	v_rcp_f32_e32 v128, v125
	v_mul_f32_e32 v125, 0xbfb8aa3b, v131
	v_exp_f32_e32 v125, v125
	s_add_u32 s45, s16, s50
	s_addc_u32 s47, s17, s51
	s_lshl_b32 s50, s5, 7
	v_add_f32_e32 v125, 1.0, v125
	v_rcp_f32_e32 v129, v125
	s_and_b32 s50, s50, 0x4000
	s_add_u32 s50, s45, s50
	s_addc_u32 s51, s47, 0
	v_pk_mul_f32 v[128:129], v[130:131], v[128:129]
	s_or_b32 s45, s5, 16
	v_pk_mul_f32 v[126:127], v[128:129], v[126:127]
	s_lshr_b32 s45, s45, 3
	v_cvt_pk_bf16_f32 v125, v126, v127
	v_mul_f32_e32 v126, 0xbfb8aa3b, v120
	v_mul_f32_e32 v127, 0xbfb8aa3b, v121
	v_exp_f32_e32 v126, v126
	v_exp_f32_e32 v127, v127
	v_or_b32_e32 v145, s5, v137
	s_and_b32 s45, s45, 10
	v_add_f32_e32 v126, 1.0, v126
	v_add_f32_e32 v127, 1.0, v127
	v_rcp_f32_e32 v126, v126
	v_rcp_f32_e32 v127, v127
	v_lshlrev_b32_e32 v132, 6, v145
	v_lshlrev_b32_e32 v146, 2, v145
	s_or_b32 s45, s45, s64
	v_pk_mul_f32 v[120:121], v[120:121], v[126:127]
	v_and_or_b32 v132, v132, s15, v142
	v_pk_mul_f32 v[116:117], v[120:121], v[116:117]
	v_and_b32_e32 v146, 32, v146
	v_cvt_pk_bf16_f32 v126, v116, v117
	v_mul_f32_e32 v116, 0xbfb8aa3b, v122
	v_mul_f32_e32 v117, 0xbfb8aa3b, v123
	v_exp_f32_e32 v116, v116
	v_exp_f32_e32 v117, v117
	s_lshl_b32 s45, s45, 10
	v_bitop3_b32 v147, v132, s65, v146 bitop3:0xde
	v_add_f32_e32 v116, 1.0, v116
	v_add_f32_e32 v117, 1.0, v117
	v_rcp_f32_e32 v116, v116
	v_rcp_f32_e32 v117, v117
	s_and_b64 vcc, exec, s[42:43]
	s_mov_b32 s68, s44
	s_mov_b32 s69, s46
	v_pk_mul_f32 v[116:117], v[122:123], v[116:117]
	s_mov_b64 s[54:55], s[40:41]
	v_pk_mul_f32 v[116:117], v[116:117], v[118:119]
	v_bitop3_b32 v118, v132, s45, v146 bitop3:0xde
	v_cvt_pk_bf16_f32 v127, v116, v117
	v_mul_f32_e32 v116, 0xbfb8aa3b, v112
	v_mul_f32_e32 v117, 0xbfb8aa3b, v113
	v_exp_f32_e32 v116, v116
	v_exp_f32_e32 v117, v117
	s_or_b32 s45, s5, 32
	s_or_b32 s5, s5, 48
	v_add_f32_e32 v116, 1.0, v116
	v_add_f32_e32 v117, 1.0, v117
	v_rcp_f32_e32 v116, v116
	v_rcp_f32_e32 v117, v117
	s_lshr_b32 s45, s45, 3
	s_lshr_b32 s5, s5, 3
	s_and_b32 s45, s45, 12
	v_pk_mul_f32 v[112:113], v[112:113], v[116:117]
	s_and_b32 s5, s5, 14
	v_pk_mul_f32 v[108:109], v[112:113], v[108:109]
	s_or_b32 s45, s45, s64
	v_cvt_pk_bf16_f32 v108, v108, v109
	v_mul_f32_e32 v109, 0xbfb8aa3b, v114
	v_exp_f32_e32 v109, v109
	s_or_b32 s5, s5, s64
	s_lshl_b32 s45, s45, 10
	s_lshl_b32 s5, s5, 10
	v_add_f32_e32 v109, 1.0, v109
	v_rcp_f32_e32 v112, v109
	v_mul_f32_e32 v109, 0xbfb8aa3b, v115
	v_exp_f32_e32 v109, v109
	global_store_dwordx4 v147, v[124:127], s[50:51]
	v_add_f32_e32 v109, 1.0, v109
	v_rcp_f32_e32 v113, v109
	s_nop 0
	v_pk_mul_f32 v[112:113], v[114:115], v[112:113]
	s_nop 0
	v_pk_mul_f32 v[110:111], v[112:113], v[110:111]
	s_nop 0
	v_cvt_pk_bf16_f32 v109, v110, v111
	v_mul_f32_e32 v110, 0xbfb8aa3b, v104
	v_mul_f32_e32 v111, 0xbfb8aa3b, v105
	v_exp_f32_e32 v110, v110
	v_exp_f32_e32 v111, v111
	v_add_f32_e32 v110, 1.0, v110
	v_add_f32_e32 v111, 1.0, v111
	v_rcp_f32_e32 v110, v110
	v_rcp_f32_e32 v111, v111
	s_nop 0
; __device__ __forceinline__ unsigned cvt_pk_bf16(float lo, float hi) { f32x2 v = {lo, hi}; bf16x2v b = __builtin_convertvector(v, bf16x2v); return __builtin_bit_cast(unsigned, b); }
; __device__ __forceinline__ float silu_f(float x) { return x * __builtin_amdgcn_rcpf(1.f + __expf(-x)); }
;     __device__ __forceinline__ void operator()(const f32x4 (&acc)[2][2][4][2], const Unit& u, int wr, int wc, int fr, int fq) const {
;     ...
;                 bf16_t* rowp = O + img_off(row0 + ai * HALF + m * 16, col0, D_FF / 64);
;                 const f32x4 g0 = acc[ai][0][m][0], g1 = acc[ai][0][m][1], u0 = acc[ai][1][m][0], u1 = acc[ai][1][m][1];
;                 u32x4 w;
;                 w.x = cvt_pk_bf16(silu_f(g0[0]) * u0[0], silu_f(g0[1]) * u0[1]); w.y = cvt_pk_bf16(silu_f(g0[2]) * u0[2], silu_f(g0[3]) * u0[3]);
;                 w.z = cvt_pk_bf16(silu_f(g1[0]) * u1[0], silu_f(g1[1]) * u1[1]); w.w = cvt_pk_bf16(silu_f(g1[2]) * u1[2], silu_f(g1[3]) * u1[3]);
;                 *(u32x4*)rowp = w;
	v_pk_mul_f32 v[104:105], v[104:105], v[110:111]
	s_nop 0
	v_pk_mul_f32 v[100:101], v[104:105], v[100:101]
	s_nop 0
	v_cvt_pk_bf16_f32 v110, v100, v101
	v_mul_f32_e32 v100, 0xbfb8aa3b, v106
	v_mul_f32_e32 v101, 0xbfb8aa3b, v107
	v_exp_f32_e32 v100, v100
	v_exp_f32_e32 v101, v101
	v_add_f32_e32 v100, 1.0, v100
	v_add_f32_e32 v101, 1.0, v101
	v_rcp_f32_e32 v100, v100
	v_rcp_f32_e32 v101, v101
	s_nop 0
	v_pk_mul_f32 v[100:101], v[106:107], v[100:101]
	s_nop 0
	v_pk_mul_f32 v[100:101], v[100:101], v[102:103]
	v_bitop3_b32 v102, v132, s45, v146 bitop3:0xde
	v_cvt_pk_bf16_f32 v111, v100, v101
	v_mul_f32_e32 v100, 0xbfb8aa3b, v96
	v_mul_f32_e32 v101, 0xbfb8aa3b, v97
	v_exp_f32_e32 v100, v100
	v_exp_f32_e32 v101, v101
	global_store_dwordx4 v118, v[108:111], s[50:51]
	v_add_f32_e32 v100, 1.0, v100
	v_add_f32_e32 v101, 1.0, v101
	v_rcp_f32_e32 v100, v100
	v_rcp_f32_e32 v101, v101
	s_nop 0
	v_pk_mul_f32 v[96:97], v[96:97], v[100:101]
	s_nop 0
	v_pk_mul_f32 v[92:93], v[96:97], v[92:93]
	s_nop 0
	v_cvt_pk_bf16_f32 v92, v92, v93
	v_mul_f32_e32 v93, 0xbfb8aa3b, v98
	v_exp_f32_e32 v93, v93
	s_nop 0
	v_add_f32_e32 v93, 1.0, v93
	v_rcp_f32_e32 v96, v93
	v_mul_f32_e32 v93, 0xbfb8aa3b, v99
	v_exp_f32_e32 v93, v93
	s_nop 0
	v_add_f32_e32 v93, 1.0, v93
	v_rcp_f32_e32 v97, v93
	s_nop 0
	v_pk_mul_f32 v[96:97], v[98:99], v[96:97]
	s_nop 0
	v_pk_mul_f32 v[94:95], v[96:97], v[94:95]
	s_nop 0
	v_cvt_pk_bf16_f32 v93, v94, v95
	v_mul_f32_e32 v94, 0xbfb8aa3b, v88
	v_mul_f32_e32 v95, 0xbfb8aa3b, v89
	v_exp_f32_e32 v94, v94
	v_exp_f32_e32 v95, v95
	v_add_f32_e32 v94, 1.0, v94
	v_add_f32_e32 v95, 1.0, v95
	v_rcp_f32_e32 v94, v94
	v_rcp_f32_e32 v95, v95
	s_nop 0
	v_pk_mul_f32 v[88:89], v[88:89], v[94:95]
	s_nop 0
	v_pk_mul_f32 v[84:85], v[88:89], v[84:85]
	s_nop 0
	v_cvt_pk_bf16_f32 v94, v84, v85
	v_mul_f32_e32 v84, 0xbfb8aa3b, v90
	v_mul_f32_e32 v85, 0xbfb8aa3b, v91
	v_exp_f32_e32 v84, v84
	v_exp_f32_e32 v85, v85
	v_add_f32_e32 v84, 1.0, v84
	v_add_f32_e32 v85, 1.0, v85
	v_rcp_f32_e32 v84, v84
	v_rcp_f32_e32 v85, v85
	s_nop 0
	v_pk_mul_f32 v[84:85], v[90:91], v[84:85]
	s_nop 0
	v_pk_mul_f32 v[84:85], v[84:85], v[86:87]
	v_bitop3_b32 v86, v132, s5, v146 bitop3:0xde
	v_cvt_pk_bf16_f32 v95, v84, v85
	v_mul_f32_e32 v84, 0xbfb8aa3b, v80
	v_mul_f32_e32 v85, 0xbfb8aa3b, v81
	v_exp_f32_e32 v84, v84
	v_exp_f32_e32 v85, v85
	global_store_dwordx4 v102, v[92:95], s[50:51]
	v_add_f32_e32 v84, 1.0, v84
	v_add_f32_e32 v85, 1.0, v85
	v_rcp_f32_e32 v84, v84
	v_rcp_f32_e32 v85, v85
	s_nop 0
	v_pk_mul_f32 v[80:81], v[80:81], v[84:85]
	s_nop 0
	v_pk_mul_f32 v[76:77], v[80:81], v[76:77]
	s_nop 0
	v_cvt_pk_bf16_f32 v76, v76, v77
	v_mul_f32_e32 v77, 0xbfb8aa3b, v82
	v_exp_f32_e32 v77, v77
	s_nop 0
	v_add_f32_e32 v77, 1.0, v77
	v_rcp_f32_e32 v80, v77
	v_mul_f32_e32 v77, 0xbfb8aa3b, v83
	v_exp_f32_e32 v77, v77
	s_nop 0
	v_add_f32_e32 v77, 1.0, v77
	v_rcp_f32_e32 v81, v77
	s_nop 0
	v_pk_mul_f32 v[80:81], v[82:83], v[80:81]
	s_nop 0
	v_pk_mul_f32 v[78:79], v[80:81], v[78:79]
	s_nop 0
	v_cvt_pk_bf16_f32 v77, v78, v79
	v_mul_f32_e32 v78, 0xbfb8aa3b, v72
	v_mul_f32_e32 v79, 0xbfb8aa3b, v73
	v_exp_f32_e32 v78, v78
	v_exp_f32_e32 v79, v79
	v_add_f32_e32 v78, 1.0, v78
	v_add_f32_e32 v79, 1.0, v79
	v_rcp_f32_e32 v78, v78
	v_rcp_f32_e32 v79, v79
	s_nop 0
	v_pk_mul_f32 v[72:73], v[72:73], v[78:79]
	s_nop 0
	v_pk_mul_f32 v[68:69], v[72:73], v[68:69]
	v_mul_f32_e32 v73, 0xbfb8aa3b, v65
	v_cvt_pk_bf16_f32 v78, v68, v69
	v_mul_f32_e32 v68, 0xbfb8aa3b, v74
	v_mul_f32_e32 v69, 0xbfb8aa3b, v75
	v_exp_f32_e32 v68, v68
	v_exp_f32_e32 v69, v69
	v_exp_f32_e32 v73, v73
	v_add_f32_e32 v68, 1.0, v68
	v_add_f32_e32 v69, 1.0, v69
	v_rcp_f32_e32 v68, v68
	v_rcp_f32_e32 v69, v69
	v_add_f32_e32 v73, 1.0, v73
	v_rcp_f32_e32 v73, v73
	v_pk_mul_f32 v[68:69], v[74:75], v[68:69]
	s_nop 0
	v_pk_mul_f32 v[68:69], v[68:69], v[70:71]
	v_add_u32_e32 v70, 0x80, v145
	v_lshlrev_b32_e32 v71, 6, v70
	v_lshlrev_b32_e32 v72, 2, v70
	v_and_or_b32 v71, v71, s15, v142
	v_and_b32_e32 v72, 32, v72
	v_bitop3_b32 v132, v71, s65, v72 bitop3:0xde
	v_mul_f32_e32 v72, 0xbfb8aa3b, v64
	v_exp_f32_e32 v72, v72
	v_cvt_pk_bf16_f32 v79, v68, v69
	v_lshrrev_b32_e32 v68, 8, v70
	v_mov_b32_e32 v69, s4
	v_add_f32_e32 v72, 1.0, v72
	v_rcp_f32_e32 v72, v72
	s_movk_i32 s4, 0x58
	v_mad_i32_i24 v68, v68, s4, v69
	v_ashrrev_i32_e32 v69, 31, v68
	v_pk_mul_f32 v[64:65], v[64:65], v[72:73]
	v_lshlrev_b64 v[68:69], 15, v[68:69]
	v_pk_mul_f32 v[60:61], v[64:65], v[60:61]
	v_lshlrev_b32_e32 v70, 7, v70
	v_cvt_pk_bf16_f32 v60, v60, v61
	v_mul_f32_e32 v61, 0xbfb8aa3b, v66
	v_exp_f32_e32 v61, v61
	v_lshl_add_u64 v[68:69], s[16:17], 0, v[68:69]
	v_and_b32_e32 v70, 0x4000, v70
	v_mov_b32_e32 v71, v133
	v_add_f32_e32 v61, 1.0, v61
	v_rcp_f32_e32 v64, v61
	v_mul_f32_e32 v61, 0xbfb8aa3b, v67
	v_exp_f32_e32 v61, v61
	v_lshl_add_u64 v[70:71], v[68:69], 0, v[70:71]
	v_lshl_add_u64 v[70:71], v[70:71], 0, v[132:133]
	s_mov_b64 s[4:5], s[48:49]
	v_add_f32_e32 v61, 1.0, v61
	v_rcp_f32_e32 v65, v61
	global_store_dwordx4 v86, v[76:79], s[50:51]
	v_pk_mul_f32 v[64:65], v[66:67], v[64:65]
	s_nop 0
	v_pk_mul_f32 v[62:63], v[64:65], v[62:63]
	s_nop 0
	v_cvt_pk_bf16_f32 v61, v62, v63
	v_mul_f32_e32 v62, 0xbfb8aa3b, v56
	v_mul_f32_e32 v63, 0xbfb8aa3b, v57
	v_exp_f32_e32 v62, v62
	v_exp_f32_e32 v63, v63
	v_add_f32_e32 v62, 1.0, v62
	v_add_f32_e32 v63, 1.0, v63
	v_rcp_f32_e32 v62, v62
	v_rcp_f32_e32 v63, v63
	s_nop 0
	v_pk_mul_f32 v[56:57], v[56:57], v[62:63]
	s_nop 0
	v_pk_mul_f32 v[52:53], v[56:57], v[52:53]
	s_nop 0
	v_cvt_pk_bf16_f32 v62, v52, v53
	v_mul_f32_e32 v52, 0xbfb8aa3b, v58
	v_mul_f32_e32 v53, 0xbfb8aa3b, v59
	v_exp_f32_e32 v52, v52
	v_exp_f32_e32 v53, v53
	v_add_f32_e32 v52, 1.0, v52
; __device__ __forceinline__ unsigned cvt_pk_bf16(float lo, float hi) { f32x2 v = {lo, hi}; bf16x2v b = __builtin_convertvector(v, bf16x2v); return __builtin_bit_cast(unsigned, b); }
; __device__ __forceinline__ float silu_f(float x) { return x * __builtin_amdgcn_rcpf(1.f + __expf(-x)); }
; #define PG8_WAIT_V(n) asm volatile("s_waitcnt vmcnt(" #n ")" ::: "memory")
; #define PG8_BAR __builtin_amdgcn_s_barrier()
;     __device__ __forceinline__ void operator()(const f32x4 (&acc)[2][2][4][2], const Unit& u, int wr, int wc, int fr, int fq) const {
;     ...
;                 bf16_t* rowp = O + img_off(row0 + ai * HALF + m * 16, col0, D_FF / 64);
;                 const f32x4 g0 = acc[ai][0][m][0], g1 = acc[ai][0][m][1], u0 = acc[ai][1][m][0], u1 = acc[ai][1][m][1];
;                 u32x4 w;
;                 w.x = cvt_pk_bf16(silu_f(g0[0]) * u0[0], silu_f(g0[1]) * u0[1]); w.y = cvt_pk_bf16(silu_f(g0[2]) * u0[2], silu_f(g0[3]) * u0[3]);
;                 w.z = cvt_pk_bf16(silu_f(g1[0]) * u1[0], silu_f(g1[1]) * u1[1]); w.w = cvt_pk_bf16(silu_f(g1[2]) * u1[2], silu_f(g1[3]) * u1[3]);
;                 *(u32x4*)rowp = w;
; template <class Epi, class Sched, int LD>
; __device__ __forceinline__ void gemm_phase(LAS unsigned char* lds, const Gemm g, const Sched& S, const Epi& E) {
;     ...
;         E(acc, cur, wr, wc, fr, fq);
;         if (!has_next) break;
; #pragma unroll
;         for (int a = 0; a < 2; ++a)
; #pragma unroll
;             for (int b = 0; b < 2; ++b)
; #pragma unroll
;                 for (int m = 0; m < 4; ++m)
; #pragma unroll
;                     for (int n = 0; n < 2; ++n) acc[a][b][m][n] = (f32x4){0.f, 0.f, 0.f, 0.f};
;         cur = nxt; cA = nA; cB = nB; ++ui;
;     }
;     PG8_WAIT_V(0);
;     if (wr == 0) PG8_BAR;
	v_add_f32_e32 v53, 1.0, v53
	v_rcp_f32_e32 v52, v52
	v_rcp_f32_e32 v53, v53
	s_nop 0
	v_pk_mul_f32 v[52:53], v[58:59], v[52:53]
	s_nop 0
	v_pk_mul_f32 v[52:53], v[52:53], v[54:55]
	s_nop 0
	v_cvt_pk_bf16_f32 v63, v52, v53
	v_add_u32_e32 v52, 0x90, v145
	v_lshrrev_b32_e32 v54, 3, v52
	v_lshlrev_b32_e32 v53, 6, v52
	v_and_or_b32 v54, v54, 10, s64
	v_lshlrev_b32_e32 v55, 2, v52
	v_and_or_b32 v53, v53, s15, v142
	v_lshlrev_b32_e32 v54, 10, v54
	v_and_b32_e32 v55, 32, v55
	v_bitop3_b32 v132, v53, v54, v55 bitop3:0xde
	v_mul_f32_e32 v54, 0xbfb8aa3b, v48
	v_mul_f32_e32 v55, 0xbfb8aa3b, v49
	v_exp_f32_e32 v54, v54
	v_exp_f32_e32 v55, v55
	v_lshlrev_b32_e32 v52, 7, v52
	v_and_b32_e32 v52, 0x4000, v52
	v_add_f32_e32 v54, 1.0, v54
	v_add_f32_e32 v55, 1.0, v55
	v_rcp_f32_e32 v54, v54
	v_rcp_f32_e32 v55, v55
	v_mov_b32_e32 v53, v133
	v_lshl_add_u64 v[52:53], v[68:69], 0, v[52:53]
	v_lshl_add_u64 v[52:53], v[52:53], 0, v[132:133]
	v_pk_mul_f32 v[48:49], v[48:49], v[54:55]
	global_store_dwordx4 v[70:71], v[60:63], off
	v_pk_mul_f32 v[44:45], v[48:49], v[44:45]
	s_nop 0
	v_cvt_pk_bf16_f32 v44, v44, v45
	v_mul_f32_e32 v45, 0xbfb8aa3b, v50
	v_exp_f32_e32 v45, v45
	s_nop 0
	v_add_f32_e32 v45, 1.0, v45
	v_rcp_f32_e32 v48, v45
	v_mul_f32_e32 v45, 0xbfb8aa3b, v51
	v_exp_f32_e32 v45, v45
	s_nop 0
	v_add_f32_e32 v45, 1.0, v45
	v_rcp_f32_e32 v49, v45
	s_nop 0
	v_pk_mul_f32 v[48:49], v[50:51], v[48:49]
	s_nop 0
	v_pk_mul_f32 v[46:47], v[48:49], v[46:47]
	s_nop 0
	v_cvt_pk_bf16_f32 v45, v46, v47
	v_mul_f32_e32 v46, 0xbfb8aa3b, v40
	v_mul_f32_e32 v47, 0xbfb8aa3b, v41
	v_exp_f32_e32 v46, v46
	v_exp_f32_e32 v47, v47
	v_add_f32_e32 v46, 1.0, v46
	v_add_f32_e32 v47, 1.0, v47
	v_rcp_f32_e32 v46, v46
	v_rcp_f32_e32 v47, v47
	s_nop 0
	v_pk_mul_f32 v[40:41], v[40:41], v[46:47]
	s_nop 0
	v_pk_mul_f32 v[36:37], v[40:41], v[36:37]
	s_nop 0
	v_cvt_pk_bf16_f32 v46, v36, v37
	v_mul_f32_e32 v36, 0xbfb8aa3b, v42
	v_mul_f32_e32 v37, 0xbfb8aa3b, v43
	v_exp_f32_e32 v36, v36
	v_exp_f32_e32 v37, v37
	v_add_f32_e32 v36, 1.0, v36
	v_add_f32_e32 v37, 1.0, v37
	v_rcp_f32_e32 v36, v36
	v_rcp_f32_e32 v37, v37
	s_nop 0
	v_pk_mul_f32 v[36:37], v[42:43], v[36:37]
	s_nop 0
	v_pk_mul_f32 v[36:37], v[36:37], v[38:39]
	s_nop 0
	v_cvt_pk_bf16_f32 v47, v36, v37
	v_add_u32_e32 v36, 0xa0, v145
	v_lshrrev_b32_e32 v38, 3, v36
	v_lshlrev_b32_e32 v37, 6, v36
	v_and_or_b32 v38, v38, 12, s64
	v_lshlrev_b32_e32 v39, 2, v36
	v_and_or_b32 v37, v37, s15, v142
	v_lshlrev_b32_e32 v38, 10, v38
	v_and_b32_e32 v39, 32, v39
	v_bitop3_b32 v132, v37, v38, v39 bitop3:0xde
	v_mul_f32_e32 v38, 0xbfb8aa3b, v32
	v_mul_f32_e32 v39, 0xbfb8aa3b, v33
	v_exp_f32_e32 v38, v38
	v_exp_f32_e32 v39, v39
	v_lshlrev_b32_e32 v36, 7, v36
	v_and_b32_e32 v36, 0x4000, v36
	v_add_f32_e32 v38, 1.0, v38
	v_add_f32_e32 v39, 1.0, v39
	v_rcp_f32_e32 v38, v38
	v_rcp_f32_e32 v39, v39
	v_mov_b32_e32 v37, v133
	v_lshl_add_u64 v[36:37], v[68:69], 0, v[36:37]
	v_lshl_add_u64 v[36:37], v[36:37], 0, v[132:133]
	v_pk_mul_f32 v[32:33], v[32:33], v[38:39]
	global_store_dwordx4 v[52:53], v[44:47], off
	v_pk_mul_f32 v[28:29], v[32:33], v[28:29]
	s_nop 0
	v_cvt_pk_bf16_f32 v28, v28, v29
	v_mul_f32_e32 v29, 0xbfb8aa3b, v34
	v_exp_f32_e32 v29, v29
	s_nop 0
	v_add_f32_e32 v29, 1.0, v29
	v_rcp_f32_e32 v32, v29
	v_mul_f32_e32 v29, 0xbfb8aa3b, v35
	v_exp_f32_e32 v29, v29
	s_nop 0
	v_add_f32_e32 v29, 1.0, v29
	v_rcp_f32_e32 v33, v29
	s_nop 0
	v_pk_mul_f32 v[32:33], v[34:35], v[32:33]
	s_nop 0
	v_pk_mul_f32 v[30:31], v[32:33], v[30:31]
	s_nop 0
	v_cvt_pk_bf16_f32 v29, v30, v31
	v_mul_f32_e32 v30, 0xbfb8aa3b, v24
	v_mul_f32_e32 v31, 0xbfb8aa3b, v25
	v_exp_f32_e32 v30, v30
	v_exp_f32_e32 v31, v31
	v_add_f32_e32 v30, 1.0, v30
	v_add_f32_e32 v31, 1.0, v31
	v_rcp_f32_e32 v30, v30
	v_rcp_f32_e32 v31, v31
	s_nop 0
	v_pk_mul_f32 v[24:25], v[24:25], v[30:31]
	s_nop 0
	v_pk_mul_f32 v[20:21], v[24:25], v[20:21]
	s_nop 0
	v_cvt_pk_bf16_f32 v30, v20, v21
	v_mul_f32_e32 v20, 0xbfb8aa3b, v26
	v_mul_f32_e32 v21, 0xbfb8aa3b, v27
	v_exp_f32_e32 v20, v20
	v_exp_f32_e32 v21, v21
	v_add_f32_e32 v20, 1.0, v20
	v_add_f32_e32 v21, 1.0, v21
	v_rcp_f32_e32 v20, v20
	v_rcp_f32_e32 v21, v21
	s_nop 0
	v_pk_mul_f32 v[20:21], v[26:27], v[20:21]
	s_nop 0
	v_pk_mul_f32 v[20:21], v[20:21], v[22:23]
	s_nop 0
	v_cvt_pk_bf16_f32 v31, v20, v21
	v_add_u32_e32 v20, 0xb0, v145
	v_lshrrev_b32_e32 v22, 3, v20
	v_lshlrev_b32_e32 v21, 6, v20
	v_and_or_b32 v22, v22, 14, s64
	v_lshlrev_b32_e32 v23, 2, v20
	v_and_or_b32 v21, v21, s15, v142
	v_lshlrev_b32_e32 v22, 10, v22
	v_and_b32_e32 v23, 32, v23
	v_bitop3_b32 v132, v21, v22, v23 bitop3:0xde
	v_mul_f32_e32 v22, 0xbfb8aa3b, v16
	v_mul_f32_e32 v23, 0xbfb8aa3b, v17
	v_exp_f32_e32 v22, v22
	v_exp_f32_e32 v23, v23
	v_lshlrev_b32_e32 v20, 7, v20
	v_and_b32_e32 v20, 0x4000, v20
	v_add_f32_e32 v22, 1.0, v22
	v_add_f32_e32 v23, 1.0, v23
	v_rcp_f32_e32 v22, v22
	v_rcp_f32_e32 v23, v23
	v_mov_b32_e32 v21, v133
	v_lshl_add_u64 v[20:21], v[68:69], 0, v[20:21]
	v_lshl_add_u64 v[20:21], v[20:21], 0, v[132:133]
	v_pk_mul_f32 v[16:17], v[16:17], v[22:23]
	global_store_dwordx4 v[36:37], v[28:31], off
	v_pk_mul_f32 v[12:13], v[16:17], v[12:13]
	s_nop 0
	v_cvt_pk_bf16_f32 v12, v12, v13
	v_mul_f32_e32 v13, 0xbfb8aa3b, v18
	v_exp_f32_e32 v13, v13
	s_nop 0
	v_add_f32_e32 v13, 1.0, v13
	v_rcp_f32_e32 v16, v13
	v_mul_f32_e32 v13, 0xbfb8aa3b, v19
	v_exp_f32_e32 v13, v13
	s_nop 0
	v_add_f32_e32 v13, 1.0, v13
	v_rcp_f32_e32 v17, v13
	s_nop 0
	v_pk_mul_f32 v[16:17], v[18:19], v[16:17]
	s_nop 0
	v_pk_mul_f32 v[14:15], v[16:17], v[14:15]
	s_nop 0
	v_cvt_pk_bf16_f32 v13, v14, v15
	v_mul_f32_e32 v14, 0xbfb8aa3b, v8
	v_mul_f32_e32 v15, 0xbfb8aa3b, v9
	v_exp_f32_e32 v14, v14
	v_exp_f32_e32 v15, v15
	v_add_f32_e32 v14, 1.0, v14
	v_add_f32_e32 v15, 1.0, v15
	v_rcp_f32_e32 v14, v14
	v_rcp_f32_e32 v15, v15
	s_nop 0
	v_pk_mul_f32 v[8:9], v[8:9], v[14:15]
	s_nop 0
	v_pk_mul_f32 v[4:5], v[8:9], v[4:5]
	s_nop 0
	v_cvt_pk_bf16_f32 v14, v4, v5
	v_mul_f32_e32 v4, 0xbfb8aa3b, v10
	v_mul_f32_e32 v5, 0xbfb8aa3b, v11
	v_exp_f32_e32 v4, v4
	v_exp_f32_e32 v5, v5
	v_add_f32_e32 v4, 1.0, v4
	v_add_f32_e32 v5, 1.0, v5
	v_rcp_f32_e32 v4, v4
	v_rcp_f32_e32 v5, v5
	s_nop 0
	v_pk_mul_f32 v[4:5], v[10:11], v[4:5]
	s_nop 0
	v_pk_mul_f32 v[4:5], v[4:5], v[6:7]
	s_nop 0
	v_cvt_pk_bf16_f32 v15, v4, v5
	global_store_dwordx4 v[20:21], v[12:15], off
	s_cbranch_vccz .LBB0_892
	s_waitcnt vmcnt(0)
	s_cmpk_gt_u32 s2, 0xff
	s_cbranch_scc1 .LBB0_903
	s_barrier
